# GEMM main loops trimmed: duplicate lgkmcnt waits dropped, loop-invariant LDS fragment addresses hoisted to VGPRs, m0->LDS-DMA wait states filled with ds_reads instead of s_nop
# speedup vs baseline: 1.0128x; 1.0058x over previous
; template <class Epi>
; __device__ __forceinline__ void gemm_phase(LAS unsigned char* lds, const Gemm g, const StaticOrder& S, const Epi& E) {
;     ...
;         const bool has_next = S.next(ui + 1, nxt);
;         const char* nA = has_next ? (const char*)g.A + (size_t)nxt.pm * tstep : cA; const char* nB = has_next ? (const char*)g.Bt + (size_t)nxt.pn * tstep : cB;
;         for (int t = 0; t < nt; t += 2) {
;             const bool last = (t == nt - 2);
;             const char* a1 = cA + (size_t)(t + 1) * kstep;
;             const char* a2 = last ? nA : cA + (size_t)(t + 2) * kstep; const char* b2 = last ? nB : cB + (size_t)(t + 2) * kstep;
;     ...
; #pragma unroll
;         for (int a = 0; a < 2; ++a)
; #pragma unroll
;             for (int b = 0; b < 2; ++b)
; #pragma unroll
;                 for (int m = 0; m < 4; ++m)
; #pragma unroll
;                     for (int n = 0; n < 2; ++n) acc[a][b][m][n] = (f32x4){0.f, 0.f, 0.f, 0.f};
;         cur = nxt; cA = nA; cB = nB; ++ui;
.LBB0_117:
	v_mov_b32_e32 v127, 0
	s_andn2_b64 vcc, exec, s[6:7]
	v_mov_b32_e32 v126, v127
	v_mov_b32_e32 v125, v127
	v_mov_b32_e32 v124, v127
	v_mov_b32_e32 v123, v127
	v_mov_b32_e32 v122, v127
	v_mov_b32_e32 v121, v127
	v_mov_b32_e32 v120, v127
	v_mov_b32_e32 v111, v127
	v_mov_b32_e32 v110, v127
	v_mov_b32_e32 v109, v127
	v_mov_b32_e32 v108, v127
	v_mov_b32_e32 v107, v127
	v_mov_b32_e32 v106, v127
	v_mov_b32_e32 v105, v127
	v_mov_b32_e32 v104, v127
	v_mov_b32_e32 v95, v127
	v_mov_b32_e32 v94, v127
	v_mov_b32_e32 v93, v127
	v_mov_b32_e32 v92, v127
	v_mov_b32_e32 v91, v127
	v_mov_b32_e32 v90, v127
	v_mov_b32_e32 v89, v127
	v_mov_b32_e32 v88, v127
	v_mov_b32_e32 v79, v127
	v_mov_b32_e32 v78, v127
	v_mov_b32_e32 v77, v127
	v_mov_b32_e32 v76, v127
	v_mov_b32_e32 v75, v127
	v_mov_b32_e32 v74, v127
	v_mov_b32_e32 v73, v127
	v_mov_b32_e32 v72, v127
	v_mov_b32_e32 v119, v127
	v_mov_b32_e32 v118, v127
	v_mov_b32_e32 v117, v127
	v_mov_b32_e32 v116, v127
	v_mov_b32_e32 v115, v127
	v_mov_b32_e32 v114, v127
	v_mov_b32_e32 v113, v127
	v_mov_b32_e32 v112, v127
	v_mov_b32_e32 v103, v127
	v_mov_b32_e32 v102, v127
	v_mov_b32_e32 v101, v127
	v_mov_b32_e32 v100, v127
	v_mov_b32_e32 v99, v127
	v_mov_b32_e32 v98, v127
	v_mov_b32_e32 v97, v127
	v_mov_b32_e32 v96, v127
	v_mov_b32_e32 v87, v127
	v_mov_b32_e32 v86, v127
	v_mov_b32_e32 v85, v127
	v_mov_b32_e32 v84, v127
	v_mov_b32_e32 v83, v127
	v_mov_b32_e32 v82, v127
	v_mov_b32_e32 v81, v127
	v_mov_b32_e32 v80, v127
	v_mov_b32_e32 v71, v127
	v_mov_b32_e32 v70, v127
	v_mov_b32_e32 v69, v127
	v_mov_b32_e32 v68, v127
	v_mov_b32_e32 v67, v127
	v_mov_b32_e32 v66, v127
	v_mov_b32_e32 v65, v127
	v_mov_b32_e32 v64, v127
	v_mov_b32_e32 v63, v127
	v_mov_b32_e32 v62, v127
	v_mov_b32_e32 v61, v127
	v_mov_b32_e32 v60, v127
	v_mov_b32_e32 v59, v127
	v_mov_b32_e32 v58, v127
	v_mov_b32_e32 v57, v127
	v_mov_b32_e32 v56, v127
	v_mov_b32_e32 v47, v127
	v_mov_b32_e32 v46, v127
	v_mov_b32_e32 v45, v127
	v_mov_b32_e32 v44, v127
	v_mov_b32_e32 v43, v127
	v_mov_b32_e32 v42, v127
	v_mov_b32_e32 v41, v127
	v_mov_b32_e32 v40, v127
	v_mov_b32_e32 v31, v127
	v_mov_b32_e32 v30, v127
	v_mov_b32_e32 v29, v127
	v_mov_b32_e32 v28, v127
	v_mov_b32_e32 v27, v127
	v_mov_b32_e32 v26, v127
	v_mov_b32_e32 v25, v127
	v_mov_b32_e32 v24, v127
	v_mov_b32_e32 v15, v127
	v_mov_b32_e32 v14, v127
	v_mov_b32_e32 v13, v127
	v_mov_b32_e32 v12, v127
	v_mov_b32_e32 v11, v127
	v_mov_b32_e32 v10, v127
	v_mov_b32_e32 v9, v127
	v_mov_b32_e32 v8, v127
	v_mov_b32_e32 v55, v127
	v_mov_b32_e32 v54, v127
	v_mov_b32_e32 v53, v127
	v_mov_b32_e32 v52, v127
	v_mov_b32_e32 v51, v127
	v_mov_b32_e32 v50, v127
	v_mov_b32_e32 v49, v127
	v_mov_b32_e32 v48, v127
	v_mov_b32_e32 v39, v127
	v_mov_b32_e32 v38, v127
	v_mov_b32_e32 v37, v127
	v_mov_b32_e32 v36, v127
	v_mov_b32_e32 v35, v127
	v_mov_b32_e32 v34, v127
	v_mov_b32_e32 v33, v127
	v_mov_b32_e32 v32, v127
	v_mov_b32_e32 v23, v127
	v_mov_b32_e32 v22, v127
	v_mov_b32_e32 v21, v127
	v_mov_b32_e32 v20, v127
	v_mov_b32_e32 v19, v127
	v_mov_b32_e32 v18, v127
	v_mov_b32_e32 v17, v127
	v_mov_b32_e32 v16, v127
	v_mov_b32_e32 v7, v127
	v_mov_b32_e32 v6, v127
	v_mov_b32_e32 v5, v127
	v_mov_b32_e32 v4, v127
	v_mov_b32_e32 v3, v127
	v_mov_b32_e32 v2, v127
	s_waitcnt lgkmcnt(0)
	v_mov_b32_e32 v1, v127
	v_mov_b32_e32 v0, v127
	s_cbranch_vccnz .LBB0_120
	s_add_u32 s39, s14, 0x100
	s_addc_u32 s40, s15, 0
	s_add_u32 s14, s16, 0x80
	v_mov_b32_e32 v0, 0
	s_addc_u32 s15, s17, 0
	s_mov_b32 s16, 0
	v_mov_b32_e32 v1, v0
	v_mov_b32_e32 v2, v0
	v_mov_b32_e32 v3, v0
	v_mov_b32_e32 v4, v0
	v_mov_b32_e32 v5, v0
	v_mov_b32_e32 v6, v0
	v_mov_b32_e32 v7, v0
	v_mov_b32_e32 v16, v0
	v_mov_b32_e32 v17, v0
	v_mov_b32_e32 v18, v0
	v_mov_b32_e32 v19, v0
	v_mov_b32_e32 v20, v0
	v_mov_b32_e32 v21, v0
	v_mov_b32_e32 v22, v0
	v_mov_b32_e32 v23, v0
	v_mov_b32_e32 v32, v0
	v_mov_b32_e32 v33, v0
	v_mov_b32_e32 v34, v0
	v_mov_b32_e32 v35, v0
	v_mov_b32_e32 v36, v0
	v_mov_b32_e32 v37, v0
	v_mov_b32_e32 v38, v0
	v_mov_b32_e32 v39, v0
	v_mov_b32_e32 v48, v0
	v_mov_b32_e32 v49, v0
	v_mov_b32_e32 v50, v0
	v_mov_b32_e32 v51, v0
	v_mov_b32_e32 v52, v0
	v_mov_b32_e32 v53, v0
	v_mov_b32_e32 v54, v0
	v_mov_b32_e32 v55, v0
	v_mov_b32_e32 v8, v0
	v_mov_b32_e32 v9, v0
	v_mov_b32_e32 v10, v0
	v_mov_b32_e32 v11, v0
	v_mov_b32_e32 v12, v0
	v_mov_b32_e32 v13, v0
	v_mov_b32_e32 v14, v0
	v_mov_b32_e32 v15, v0
	v_mov_b32_e32 v24, v0
	v_mov_b32_e32 v25, v0
	v_mov_b32_e32 v26, v0
	v_mov_b32_e32 v27, v0
	v_mov_b32_e32 v28, v0
	v_mov_b32_e32 v29, v0
	v_mov_b32_e32 v30, v0
	v_mov_b32_e32 v31, v0
	v_mov_b32_e32 v40, v0
	v_mov_b32_e32 v41, v0
	v_mov_b32_e32 v42, v0
	v_mov_b32_e32 v43, v0
	v_mov_b32_e32 v44, v0
	v_mov_b32_e32 v45, v0
	v_mov_b32_e32 v46, v0
	v_mov_b32_e32 v47, v0
	v_mov_b32_e32 v56, v0
	v_mov_b32_e32 v57, v0
	v_mov_b32_e32 v58, v0
	v_mov_b32_e32 v59, v0
	v_mov_b32_e32 v60, v0
	v_mov_b32_e32 v61, v0
	v_mov_b32_e32 v62, v0
	v_mov_b32_e32 v63, v0
	v_mov_b32_e32 v64, v0
	v_mov_b32_e32 v65, v0
	v_mov_b32_e32 v66, v0
	v_mov_b32_e32 v67, v0
	v_mov_b32_e32 v68, v0
	v_mov_b32_e32 v69, v0
	v_mov_b32_e32 v70, v0
	v_mov_b32_e32 v71, v0
	v_mov_b32_e32 v80, v0
	v_mov_b32_e32 v81, v0
	v_mov_b32_e32 v82, v0
	v_mov_b32_e32 v83, v0
	v_mov_b32_e32 v84, v0
	v_mov_b32_e32 v85, v0
	v_mov_b32_e32 v86, v0
	v_mov_b32_e32 v87, v0
	v_mov_b32_e32 v96, v0
	v_mov_b32_e32 v97, v0
	v_mov_b32_e32 v98, v0
	v_mov_b32_e32 v99, v0
	v_mov_b32_e32 v100, v0
	v_mov_b32_e32 v101, v0
	v_mov_b32_e32 v102, v0
	v_mov_b32_e32 v103, v0
	v_mov_b32_e32 v112, v0
	v_mov_b32_e32 v113, v0
	v_mov_b32_e32 v114, v0
	v_mov_b32_e32 v115, v0
	v_mov_b32_e32 v116, v0
	v_mov_b32_e32 v117, v0
	v_mov_b32_e32 v118, v0
	v_mov_b32_e32 v119, v0
	v_mov_b32_e32 v72, v0
	v_mov_b32_e32 v73, v0
	v_mov_b32_e32 v74, v0
	v_mov_b32_e32 v75, v0
	v_mov_b32_e32 v76, v0
	v_mov_b32_e32 v77, v0
	v_mov_b32_e32 v78, v0
	v_mov_b32_e32 v79, v0
	v_mov_b32_e32 v88, v0
	v_mov_b32_e32 v89, v0
	v_mov_b32_e32 v90, v0
	v_mov_b32_e32 v91, v0
	v_mov_b32_e32 v92, v0
	v_mov_b32_e32 v93, v0
	v_mov_b32_e32 v94, v0
	v_mov_b32_e32 v95, v0
	v_mov_b32_e32 v104, v0
	v_mov_b32_e32 v105, v0
	v_mov_b32_e32 v106, v0
	v_mov_b32_e32 v107, v0
	v_mov_b32_e32 v108, v0
	v_mov_b32_e32 v109, v0
	v_mov_b32_e32 v110, v0
	v_mov_b32_e32 v111, v0
	v_mov_b32_e32 v120, v0
	v_mov_b32_e32 v121, v0
	v_mov_b32_e32 v122, v0
	v_mov_b32_e32 v123, v0
	v_mov_b32_e32 v124, v0
	v_mov_b32_e32 v125, v0
	v_mov_b32_e32 v126, v0
	v_mov_b32_e32 v127, v0
	s_mov_b64 s[44:45], 0x80
	v_add_u32_e32 v224, 0x10000, v245
	v_add_u32_e32 v225, 0x14000, v245
	v_add_u32_e32 v226, 0x18000, v245
	v_add_u32_e32 v227, 0x1c000, v245
; #define PG8_STAGE(bufoff, gbase, voff) do { _Pragma("unroll") for (int _i = 0; _i < 2; ++_i) \
;         __builtin_amdgcn_global_load_lds((const unsigned*)((const char*)(gbase) + (voff)[_i]), (LAS unsigned*)(lds + (bufoff) + ldsw + _i * 8192), 16, 0, 0); } while (0)
; #define PG8_LDA(dst, b, h) do { _Pragma("unroll") for (int m = 0; m < 4; ++m) _Pragma("unroll") for (int k = 0; k < 2; ++k) dst[m][k] = *(const LAS bf16x8*)(lds + PG8_SA(b, h) + aoff + m * 2048 + k * 1024); } while (0)
; #define PG8_LDB(dst, b, h) do { _Pragma("unroll") for (int n = 0; n < 2; ++n) _Pragma("unroll") for (int k = 0; k < 2; ++k) dst[n][k] = *(const LAS bf16x8*)(lds + PG8_SB(b, h) + boff + n * 2048 + k * 1024); } while (0)
; #define PG8_WAIT_V(n) asm volatile("s_waitcnt vmcnt(" #n ")" ::: "memory")
; #define PG8_WAIT_L(n) asm volatile("s_waitcnt lgkmcnt(" #n ")" ::: "memory")
; #define PG8_BAR __builtin_amdgcn_s_barrier()
; #define PG8_SCHED __builtin_amdgcn_sched_barrier(0)
; template <class Epi>
; __device__ __forceinline__ void gemm_phase(LAS unsigned char* lds, const Gemm g, const StaticOrder& S, const Epi& E) {
;     ...
;         const bool has_next = S.next(ui + 1, nxt);
;         const char* nA = has_next ? (const char*)g.A + (size_t)nxt.pm * tstep : cA; const char* nB = has_next ? (const char*)g.Bt + (size_t)nxt.pn * tstep : cB;
;         for (int t = 0; t < nt; t += 2) {
;             const bool last = (t == nt - 2);
;             const char* a1 = cA + (size_t)(t + 1) * kstep;
;             const char* a2 = last ? nA : cA + (size_t)(t + 2) * kstep; const char* b2 = last ? nB : cB + (size_t)(t + 2) * kstep;
;             const char* a3 = a2 + kstep; const char* b3 = b2 + kstep;
;             PG8_LDB(B0, 0, 0); PG8_SCHED; PG8_LDA(At, 0, 0); PG8_STAGE(PG8_SA(1, 1), a1 + hstep, voffA);
;             PG8_WAIT_L(8); PG8_BAR; PG8_WAIT_L(0); PG8_MMA(0, 0, At, B0); PG8_BAR; PG8_SCHED;
;             PG8_LDB(B1, 0, 1); PG8_STAGE(PG8_SB(0, 0), b2, voffB);
;             PG8_BAR; PG8_WAIT_L(0); PG8_MMA(0, 1, At, B1); PG8_BAR;
;             PG8_LDA(At, 0, 1); PG8_STAGE(PG8_SA(0, 0), a2, voffA);
;             PG8_BAR; PG8_WAIT_L(0); PG8_MMA(1, 0, At, B0); PG8_BAR; PG8_SCHED;
;             PG8_STAGE(PG8_SB(0, 1), b2 + hstep, voffB);
;             PG8_WAIT_V(6); PG8_BAR; PG8_MMA(1, 1, At, B1); PG8_BAR;
.LBB0_119:
	s_add_i32 s41, s16, 2
	s_add_u32 s18, s14, 0x80
	s_addc_u32 s17, s15, 0
	s_add_i32 s42, 0, 0x10000
	ds_read_b128 v[128:131], v224
	ds_read_b128 v[132:135], v224 offset:1024
	ds_read_b128 v[136:139], v224 offset:2048
	ds_read_b128 v[140:143], v224 offset:3072
	s_cmp_eq_u32 s31, s16
	s_cselect_b32 s16, s10, s18
	s_cselect_b32 s17, s11, s17
	s_cselect_b32 s19, s13, s40
	s_cselect_b32 s18, s12, s39
	s_add_i32 m0, s24, 0xc000
	ds_read_b128 v[144:147], v247
	ds_read_b128 v[148:151], v247 offset:1024
	ds_read_b128 v[152:155], v247 offset:2048
	ds_read_b128 v[156:159], v247 offset:3072
	ds_read_b128 v[160:163], v247 offset:4096
	ds_read_b128 v[164:167], v247 offset:5120
	ds_read_b128 v[168:171], v247 offset:6144
	global_load_lds_dwordx4 v210, s[14:15]
	s_add_i32 m0, s24, 0xe000
	ds_read_b128 v[172:175], v247 offset:7168
	global_load_lds_dwordx4 v208, s[14:15]
	s_waitcnt lgkmcnt(8)
	s_barrier
	s_waitcnt lgkmcnt(0)
	v_mfma_f32_16x16x32_bf16 v[124:127], v[128:131], v[144:147], v[124:127]
	v_mfma_f32_16x16x32_bf16 v[120:123], v[136:139], v[144:147], v[120:123]
	v_mfma_f32_16x16x32_bf16 v[108:111], v[128:131], v[152:155], v[108:111]
	v_mfma_f32_16x16x32_bf16 v[104:107], v[136:139], v[152:155], v[104:107]
	v_mfma_f32_16x16x32_bf16 v[92:95], v[128:131], v[160:163], v[92:95]
	v_mfma_f32_16x16x32_bf16 v[88:91], v[136:139], v[160:163], v[88:91]
	v_mfma_f32_16x16x32_bf16 v[76:79], v[128:131], v[168:171], v[76:79]
	v_mfma_f32_16x16x32_bf16 v[72:75], v[136:139], v[168:171], v[72:75]
	v_mfma_f32_16x16x32_bf16 v[124:127], v[132:135], v[148:151], v[124:127]
	v_mfma_f32_16x16x32_bf16 v[120:123], v[140:143], v[148:151], v[120:123]
	v_mfma_f32_16x16x32_bf16 v[108:111], v[132:135], v[156:159], v[108:111]
	v_mfma_f32_16x16x32_bf16 v[104:107], v[140:143], v[156:159], v[104:107]
	v_mfma_f32_16x16x32_bf16 v[92:95], v[132:135], v[164:167], v[92:95]
	v_mfma_f32_16x16x32_bf16 v[88:91], v[140:143], v[164:167], v[88:91]
	v_mfma_f32_16x16x32_bf16 v[76:79], v[132:135], v[172:175], v[76:79]
	v_mfma_f32_16x16x32_bf16 v[72:75], v[140:143], v[172:175], v[72:75]
	s_barrier
	s_add_i32 s43, 0, 0x14000
	s_add_i32 s42, s42, s23
	s_add_u32 s80, s18, 0x80
	s_addc_u32 s81, s19, 0
	s_mov_b32 m0, s42
	ds_read_b128 v[176:179], v225
	ds_read_b128 v[180:183], v225 offset:1024
	ds_read_b128 v[184:187], v225 offset:2048
	global_load_lds_dwordx4 v194, s[18:19]
	s_add_i32 m0, s42, 0x2000
	ds_read_b128 v[188:191], v225 offset:3072
	global_load_lds_dwordx4 v206, s[18:19]
	s_barrier
	s_waitcnt lgkmcnt(0)
	v_mfma_f32_16x16x32_bf16 v[116:119], v[176:179], v[144:147], v[116:119]
	v_mfma_f32_16x16x32_bf16 v[112:115], v[184:187], v[144:147], v[112:115]
	v_mfma_f32_16x16x32_bf16 v[100:103], v[176:179], v[152:155], v[100:103]
	v_mfma_f32_16x16x32_bf16 v[96:99], v[184:187], v[152:155], v[96:99]
	v_mfma_f32_16x16x32_bf16 v[84:87], v[176:179], v[160:163], v[84:87]
	v_mfma_f32_16x16x32_bf16 v[80:83], v[184:187], v[160:163], v[80:83]
	v_mfma_f32_16x16x32_bf16 v[68:71], v[176:179], v[168:171], v[68:71]
	v_mfma_f32_16x16x32_bf16 v[64:67], v[184:187], v[168:171], v[64:67]
	v_mfma_f32_16x16x32_bf16 v[116:119], v[180:183], v[148:151], v[116:119]
	v_mfma_f32_16x16x32_bf16 v[112:115], v[188:191], v[148:151], v[112:115]
	v_mfma_f32_16x16x32_bf16 v[100:103], v[180:183], v[156:159], v[100:103]
	v_mfma_f32_16x16x32_bf16 v[96:99], v[188:191], v[156:159], v[96:99]
	v_mfma_f32_16x16x32_bf16 v[84:87], v[180:183], v[164:167], v[84:87]
	v_mfma_f32_16x16x32_bf16 v[80:83], v[188:191], v[164:167], v[80:83]
	v_mfma_f32_16x16x32_bf16 v[68:71], v[180:183], v[172:175], v[68:71]
	v_mfma_f32_16x16x32_bf16 v[64:67], v[188:191], v[172:175], v[64:67]
	s_mov_b32 m0, s24
	s_add_u32 s82, s16, 0x80
	s_addc_u32 s83, s17, 0
	s_barrier
	ds_read_b128 v[144:147], v247 offset:16384
	ds_read_b128 v[148:151], v247 offset:17408
	ds_read_b128 v[152:155], v247 offset:18432
	ds_read_b128 v[156:159], v247 offset:19456
	ds_read_b128 v[160:163], v247 offset:20480
	ds_read_b128 v[164:167], v247 offset:21504
	ds_read_b128 v[168:171], v247 offset:22528
	global_load_lds_dwordx4 v202, s[16:17]
	s_mov_b32 m0, s25
	ds_read_b128 v[172:175], v247 offset:23552
	global_load_lds_dwordx4 v204, s[16:17]
	s_barrier
	s_waitcnt lgkmcnt(0)
	v_mfma_f32_16x16x32_bf16 v[60:63], v[128:131], v[144:147], v[60:63]
	v_mfma_f32_16x16x32_bf16 v[56:59], v[136:139], v[144:147], v[56:59]
	v_mfma_f32_16x16x32_bf16 v[44:47], v[128:131], v[152:155], v[44:47]
	v_mfma_f32_16x16x32_bf16 v[40:43], v[136:139], v[152:155], v[40:43]
	v_mfma_f32_16x16x32_bf16 v[28:31], v[128:131], v[160:163], v[28:31]
	v_mfma_f32_16x16x32_bf16 v[24:27], v[136:139], v[160:163], v[24:27]
	v_mfma_f32_16x16x32_bf16 v[12:15], v[128:131], v[168:171], v[12:15]
	v_mfma_f32_16x16x32_bf16 v[8:11], v[136:139], v[168:171], v[8:11]
	v_mfma_f32_16x16x32_bf16 v[60:63], v[132:135], v[148:151], v[60:63]
	v_mfma_f32_16x16x32_bf16 v[56:59], v[140:143], v[148:151], v[56:59]
	v_mfma_f32_16x16x32_bf16 v[44:47], v[132:135], v[156:159], v[44:47]
	v_mfma_f32_16x16x32_bf16 v[40:43], v[140:143], v[156:159], v[40:43]
	v_mfma_f32_16x16x32_bf16 v[28:31], v[132:135], v[164:167], v[28:31]
	v_mfma_f32_16x16x32_bf16 v[24:27], v[140:143], v[164:167], v[24:27]
	v_mfma_f32_16x16x32_bf16 v[12:15], v[132:135], v[172:175], v[12:15]
	v_mfma_f32_16x16x32_bf16 v[8:11], v[140:143], v[172:175], v[8:11]
	s_barrier
	s_add_u32 s18, s18, s0
	s_addc_u32 s19, s19, s1
	s_add_i32 s42, s43, s23
	s_add_u32 s84, s18, 0x80
	s_mov_b32 m0, s42
	s_addc_u32 s85, s19, 0
	global_load_lds_dwordx4 v194, s[18:19]
	s_add_i32 m0, s42, 0x2000
	s_nop 0
	global_load_lds_dwordx4 v206, s[18:19]
	s_waitcnt vmcnt(6)
	s_barrier
; #define PG8_STAGE(bufoff, gbase, voff) do { _Pragma("unroll") for (int _i = 0; _i < 2; ++_i) \
;         __builtin_amdgcn_global_load_lds((const unsigned*)((const char*)(gbase) + (voff)[_i]), (LAS unsigned*)(lds + (bufoff) + ldsw + _i * 8192), 16, 0, 0); } while (0)
; #define PG8_LDA(dst, b, h) do { _Pragma("unroll") for (int m = 0; m < 4; ++m) _Pragma("unroll") for (int k = 0; k < 2; ++k) dst[m][k] = *(const LAS bf16x8*)(lds + PG8_SA(b, h) + aoff + m * 2048 + k * 1024); } while (0)
; #define PG8_LDB(dst, b, h) do { _Pragma("unroll") for (int n = 0; n < 2; ++n) _Pragma("unroll") for (int k = 0; k < 2; ++k) dst[n][k] = *(const LAS bf16x8*)(lds + PG8_SB(b, h) + boff + n * 2048 + k * 1024); } while (0)
; #define PG8_MMA(ai, bj, At, Bt) do { __builtin_amdgcn_s_setprio(1); _Pragma("unroll") for (int m = 0; m < 4; ++m) _Pragma("unroll") for (int n = 0; n < 2; ++n) _Pragma("unroll") for (int k = 0; k < 2; ++k) \
;         acc[ai][bj][m][n] = __builtin_amdgcn_mfma_f32_16x16x32_bf16(Bt[n][k], At[m][k], acc[ai][bj][m][n], 0, 0, 0); __builtin_amdgcn_s_setprio(0); } while (0)
; #define PG8_WAIT_V(n) asm volatile("s_waitcnt vmcnt(" #n ")" ::: "memory")
; #define PG8_WAIT_L(n) asm volatile("s_waitcnt lgkmcnt(" #n ")" ::: "memory")
; #define PG8_BAR __builtin_amdgcn_s_barrier()
; #define PG8_SCHED __builtin_amdgcn_sched_barrier(0)
; template <class Epi>
; __device__ __forceinline__ void gemm_phase(LAS unsigned char* lds, const Gemm g, const StaticOrder& S, const Epi& E) {
;     ...
;             PG8_WAIT_V(6); PG8_BAR; PG8_MMA(1, 1, At, B1); PG8_BAR;
;             PG8_LDB(B0, 1, 0); PG8_SCHED; PG8_LDA(At, 1, 0); PG8_STAGE(PG8_SA(0, 1), a2 + hstep, voffA);
;             PG8_WAIT_L(8); PG8_BAR; PG8_WAIT_L(0); PG8_MMA(0, 0, At, B0); PG8_BAR; PG8_SCHED;
;             PG8_LDB(B1, 1, 1); PG8_STAGE(PG8_SB(1, 0), b3, voffB);
	v_mfma_f32_16x16x32_bf16 v[52:55], v[176:179], v[144:147], v[52:55]
	v_mfma_f32_16x16x32_bf16 v[48:51], v[184:187], v[144:147], v[48:51]
	v_mfma_f32_16x16x32_bf16 v[36:39], v[176:179], v[152:155], v[36:39]
	v_mfma_f32_16x16x32_bf16 v[32:35], v[184:187], v[152:155], v[32:35]
	v_mfma_f32_16x16x32_bf16 v[20:23], v[176:179], v[160:163], v[20:23]
	v_mfma_f32_16x16x32_bf16 v[16:19], v[184:187], v[160:163], v[16:19]
	v_mfma_f32_16x16x32_bf16 v[4:7], v[176:179], v[168:171], v[4:7]
	v_mfma_f32_16x16x32_bf16 v[0:3], v[184:187], v[168:171], v[0:3]
	v_mfma_f32_16x16x32_bf16 v[52:55], v[180:183], v[148:151], v[52:55]
	v_mfma_f32_16x16x32_bf16 v[48:51], v[188:191], v[148:151], v[48:51]
	v_mfma_f32_16x16x32_bf16 v[36:39], v[180:183], v[156:159], v[36:39]
	v_mfma_f32_16x16x32_bf16 v[32:35], v[188:191], v[156:159], v[32:35]
	v_mfma_f32_16x16x32_bf16 v[20:23], v[180:183], v[164:167], v[20:23]
	v_mfma_f32_16x16x32_bf16 v[16:19], v[188:191], v[164:167], v[16:19]
	v_mfma_f32_16x16x32_bf16 v[4:7], v[180:183], v[172:175], v[4:7]
	v_mfma_f32_16x16x32_bf16 v[0:3], v[188:191], v[172:175], v[0:3]
	s_add_i32 s18, 0, 0x18000
	s_barrier
	ds_read_b128 v[128:131], v226
	ds_read_b128 v[132:135], v226 offset:1024
	ds_read_b128 v[136:139], v226 offset:2048
	ds_read_b128 v[140:143], v226 offset:3072
	s_add_u32 s16, s16, s0
	s_addc_u32 s17, s17, s1
	s_mov_b32 m0, s26
	ds_read_b128 v[144:147], v247 offset:32768
	ds_read_b128 v[148:151], v247 offset:33792
	ds_read_b128 v[152:155], v247 offset:34816
	ds_read_b128 v[156:159], v247 offset:35840
	ds_read_b128 v[160:163], v247 offset:36864
	ds_read_b128 v[164:167], v247 offset:37888
	ds_read_b128 v[168:171], v247 offset:38912
	global_load_lds_dwordx4 v202, s[16:17]
	s_mov_b32 m0, s27
	ds_read_b128 v[172:175], v247 offset:39936
	global_load_lds_dwordx4 v204, s[16:17]
	s_waitcnt lgkmcnt(8)
	s_barrier
	s_waitcnt lgkmcnt(0)
	v_mfma_f32_16x16x32_bf16 v[124:127], v[128:131], v[144:147], v[124:127]
	v_mfma_f32_16x16x32_bf16 v[120:123], v[136:139], v[144:147], v[120:123]
	v_mfma_f32_16x16x32_bf16 v[108:111], v[128:131], v[152:155], v[108:111]
	v_mfma_f32_16x16x32_bf16 v[104:107], v[136:139], v[152:155], v[104:107]
	v_mfma_f32_16x16x32_bf16 v[92:95], v[128:131], v[160:163], v[92:95]
	v_mfma_f32_16x16x32_bf16 v[88:91], v[136:139], v[160:163], v[88:91]
	v_mfma_f32_16x16x32_bf16 v[76:79], v[128:131], v[168:171], v[76:79]
	v_mfma_f32_16x16x32_bf16 v[72:75], v[136:139], v[168:171], v[72:75]
	v_mfma_f32_16x16x32_bf16 v[124:127], v[132:135], v[148:151], v[124:127]
	v_mfma_f32_16x16x32_bf16 v[120:123], v[140:143], v[148:151], v[120:123]
	v_mfma_f32_16x16x32_bf16 v[108:111], v[132:135], v[156:159], v[108:111]
	v_mfma_f32_16x16x32_bf16 v[104:107], v[140:143], v[156:159], v[104:107]
	v_mfma_f32_16x16x32_bf16 v[92:95], v[132:135], v[164:167], v[92:95]
	v_mfma_f32_16x16x32_bf16 v[88:91], v[140:143], v[164:167], v[88:91]
	v_mfma_f32_16x16x32_bf16 v[76:79], v[132:135], v[172:175], v[76:79]
	v_mfma_f32_16x16x32_bf16 v[72:75], v[140:143], v[172:175], v[72:75]
	s_barrier
	s_add_i32 s16, 0, 0x1c000
	s_add_i32 s17, s18, s23
	s_mov_b32 m0, s17
	ds_read_b128 v[176:179], v227
	ds_read_b128 v[180:183], v227 offset:1024
	ds_read_b128 v[184:187], v227 offset:2048
	global_load_lds_dwordx4 v194, s[80:81]
	s_add_i32 m0, s17, 0x2000
	ds_read_b128 v[188:191], v227 offset:3072
	global_load_lds_dwordx4 v206, s[80:81]
	s_barrier
; #define PG8_STAGE(bufoff, gbase, voff) do { _Pragma("unroll") for (int _i = 0; _i < 2; ++_i) \
;         __builtin_amdgcn_global_load_lds((const unsigned*)((const char*)(gbase) + (voff)[_i]), (LAS unsigned*)(lds + (bufoff) + ldsw + _i * 8192), 16, 0, 0); } while (0)
; #define PG8_LDA(dst, b, h) do { _Pragma("unroll") for (int m = 0; m < 4; ++m) _Pragma("unroll") for (int k = 0; k < 2; ++k) dst[m][k] = *(const LAS bf16x8*)(lds + PG8_SA(b, h) + aoff + m * 2048 + k * 1024); } while (0)
; #define PG8_MMA(ai, bj, At, Bt) do { __builtin_amdgcn_s_setprio(1); _Pragma("unroll") for (int m = 0; m < 4; ++m) _Pragma("unroll") for (int n = 0; n < 2; ++n) _Pragma("unroll") for (int k = 0; k < 2; ++k) \
;         acc[ai][bj][m][n] = __builtin_amdgcn_mfma_f32_16x16x32_bf16(Bt[n][k], At[m][k], acc[ai][bj][m][n], 0, 0, 0); __builtin_amdgcn_s_setprio(0); } while (0)
; #define PG8_WAIT_V(n) asm volatile("s_waitcnt vmcnt(" #n ")" ::: "memory")
; #define PG8_WAIT_L(n) asm volatile("s_waitcnt lgkmcnt(" #n ")" ::: "memory")
; #define PG8_BAR __builtin_amdgcn_s_barrier()
; #define PG8_SCHED __builtin_amdgcn_sched_barrier(0)
; template <class Epi>
; __device__ __forceinline__ void gemm_phase(LAS unsigned char* lds, const Gemm g, const StaticOrder& S, const Epi& E) {
;     ...
;             PG8_BAR; PG8_WAIT_L(0); PG8_MMA(0, 1, At, B1); PG8_BAR;
;             PG8_LDA(At, 1, 1); PG8_STAGE(PG8_SA(1, 0), a3, voffA);
;             PG8_BAR; PG8_WAIT_L(0); PG8_MMA(1, 0, At, B0); PG8_BAR; PG8_SCHED;
;             PG8_STAGE(PG8_SB(1, 1), b3 + hstep, voffB);
;             PG8_WAIT_V(6); PG8_BAR; PG8_MMA(1, 1, At, B1); PG8_BAR;
;         }
	s_waitcnt lgkmcnt(0)
	v_mfma_f32_16x16x32_bf16 v[116:119], v[176:179], v[144:147], v[116:119]
	v_mfma_f32_16x16x32_bf16 v[112:115], v[184:187], v[144:147], v[112:115]
	v_mfma_f32_16x16x32_bf16 v[100:103], v[176:179], v[152:155], v[100:103]
	v_mfma_f32_16x16x32_bf16 v[96:99], v[184:187], v[152:155], v[96:99]
	v_mfma_f32_16x16x32_bf16 v[84:87], v[176:179], v[160:163], v[84:87]
	v_mfma_f32_16x16x32_bf16 v[80:83], v[184:187], v[160:163], v[80:83]
	v_mfma_f32_16x16x32_bf16 v[68:71], v[176:179], v[168:171], v[68:71]
	v_mfma_f32_16x16x32_bf16 v[64:67], v[184:187], v[168:171], v[64:67]
	v_mfma_f32_16x16x32_bf16 v[116:119], v[180:183], v[148:151], v[116:119]
	v_mfma_f32_16x16x32_bf16 v[112:115], v[188:191], v[148:151], v[112:115]
	v_mfma_f32_16x16x32_bf16 v[100:103], v[180:183], v[156:159], v[100:103]
	v_mfma_f32_16x16x32_bf16 v[96:99], v[188:191], v[156:159], v[96:99]
	v_mfma_f32_16x16x32_bf16 v[84:87], v[180:183], v[164:167], v[84:87]
	v_mfma_f32_16x16x32_bf16 v[80:83], v[188:191], v[164:167], v[80:83]
	v_mfma_f32_16x16x32_bf16 v[68:71], v[180:183], v[172:175], v[68:71]
	v_mfma_f32_16x16x32_bf16 v[64:67], v[188:191], v[172:175], v[64:67]
	s_mov_b32 m0, s28
	s_barrier
	ds_read_b128 v[144:147], v247 offset:49152
	ds_read_b128 v[148:151], v247 offset:50176
	ds_read_b128 v[152:155], v247 offset:51200
	ds_read_b128 v[156:159], v247 offset:52224
	ds_read_b128 v[160:163], v247 offset:53248
	ds_read_b128 v[164:167], v247 offset:54272
	ds_read_b128 v[168:171], v247 offset:55296
	global_load_lds_dwordx4 v202, s[82:83]
	s_mov_b32 m0, s29
	ds_read_b128 v[172:175], v247 offset:56320
	global_load_lds_dwordx4 v204, s[82:83]
	s_barrier
	s_waitcnt lgkmcnt(0)
	v_mfma_f32_16x16x32_bf16 v[60:63], v[128:131], v[144:147], v[60:63]
	v_mfma_f32_16x16x32_bf16 v[56:59], v[136:139], v[144:147], v[56:59]
	v_mfma_f32_16x16x32_bf16 v[44:47], v[128:131], v[152:155], v[44:47]
	v_mfma_f32_16x16x32_bf16 v[40:43], v[136:139], v[152:155], v[40:43]
	v_mfma_f32_16x16x32_bf16 v[28:31], v[128:131], v[160:163], v[28:31]
	v_mfma_f32_16x16x32_bf16 v[24:27], v[136:139], v[160:163], v[24:27]
	v_mfma_f32_16x16x32_bf16 v[12:15], v[128:131], v[168:171], v[12:15]
	v_mfma_f32_16x16x32_bf16 v[8:11], v[136:139], v[168:171], v[8:11]
	v_mfma_f32_16x16x32_bf16 v[60:63], v[132:135], v[148:151], v[60:63]
	v_mfma_f32_16x16x32_bf16 v[56:59], v[140:143], v[148:151], v[56:59]
	v_mfma_f32_16x16x32_bf16 v[44:47], v[132:135], v[156:159], v[44:47]
	v_mfma_f32_16x16x32_bf16 v[40:43], v[140:143], v[156:159], v[40:43]
	v_mfma_f32_16x16x32_bf16 v[28:31], v[132:135], v[164:167], v[28:31]
	v_mfma_f32_16x16x32_bf16 v[24:27], v[140:143], v[164:167], v[24:27]
	v_mfma_f32_16x16x32_bf16 v[12:15], v[132:135], v[172:175], v[12:15]
	v_mfma_f32_16x16x32_bf16 v[8:11], v[140:143], v[172:175], v[8:11]
	s_barrier
	s_add_i32 s16, s16, s23
	s_mov_b32 m0, s16
	s_nop 0
	global_load_lds_dwordx4 v194, s[84:85]
	s_add_i32 m0, s16, 0x2000
	s_nop 0
	global_load_lds_dwordx4 v206, s[84:85]
	s_waitcnt vmcnt(6)
	s_barrier
	v_mfma_f32_16x16x32_bf16 v[52:55], v[176:179], v[144:147], v[52:55]
	v_mfma_f32_16x16x32_bf16 v[48:51], v[184:187], v[144:147], v[48:51]
	v_mfma_f32_16x16x32_bf16 v[36:39], v[176:179], v[152:155], v[36:39]
	v_mfma_f32_16x16x32_bf16 v[32:35], v[184:187], v[152:155], v[32:35]
	v_mfma_f32_16x16x32_bf16 v[20:23], v[176:179], v[160:163], v[20:23]
	v_mfma_f32_16x16x32_bf16 v[16:19], v[184:187], v[160:163], v[16:19]
	v_mfma_f32_16x16x32_bf16 v[4:7], v[176:179], v[168:171], v[4:7]
	v_mfma_f32_16x16x32_bf16 v[0:3], v[184:187], v[168:171], v[0:3]
	v_mfma_f32_16x16x32_bf16 v[52:55], v[180:183], v[148:151], v[52:55]
	v_mfma_f32_16x16x32_bf16 v[48:51], v[188:191], v[148:151], v[48:51]
	v_mfma_f32_16x16x32_bf16 v[36:39], v[180:183], v[156:159], v[36:39]
	v_mfma_f32_16x16x32_bf16 v[32:35], v[188:191], v[156:159], v[32:35]
	v_mfma_f32_16x16x32_bf16 v[20:23], v[180:183], v[164:167], v[20:23]
	v_mfma_f32_16x16x32_bf16 v[16:19], v[188:191], v[164:167], v[16:19]
	v_mfma_f32_16x16x32_bf16 v[4:7], v[180:183], v[172:175], v[4:7]
	v_mfma_f32_16x16x32_bf16 v[0:3], v[188:191], v[172:175], v[0:3]
	s_add_u32 s39, s39, 0x100
	s_addc_u32 s40, s40, 0
	s_add_u32 s14, s14, 0x100
	s_addc_u32 s15, s15, 0
	s_cmp_ge_i32 s41, s30
	s_mov_b32 s16, s41
	s_barrier
	s_cbranch_scc0 .LBB0_119

; template <class Epi>
; __device__ __forceinline__ void gemm_phase(LAS unsigned char* lds, const Gemm g, const StaticOrder& S, const Epi& E) {
;     ...
;     f32x4 acc[2][2][4][2];
; #pragma unroll
;     for (int a = 0; a < 2; ++a)
; #pragma unroll
;         for (int b = 0; b < 2; ++b)
; #pragma unroll
;             for (int m = 0; m < 4; ++m)
; #pragma unroll
;                 for (int n = 0; n < 2; ++n) acc[a][b][m][n] = (f32x4){0.f, 0.f, 0.f, 0.f};
;     ...
; #pragma unroll
;         for (int a = 0; a < 2; ++a)
; #pragma unroll
;             for (int b = 0; b < 2; ++b)
; #pragma unroll
;                 for (int m = 0; m < 4; ++m)
; #pragma unroll
;                     for (int n = 0; n < 2; ++n) acc[a][b][m][n] = (f32x4){0.f, 0.f, 0.f, 0.f};
;         cur = nxt; cA = nA; cB = nB; ++ui;
.LBB0_163:
	v_mov_b32_e32 v127, 0
	s_andn2_b64 vcc, exec, s[6:7]
	v_mov_b32_e32 v126, v127
	v_mov_b32_e32 v125, v127
	v_mov_b32_e32 v124, v127
	v_mov_b32_e32 v123, v127
	v_mov_b32_e32 v122, v127
	v_mov_b32_e32 v121, v127
	v_mov_b32_e32 v120, v127
	v_mov_b32_e32 v111, v127
	v_mov_b32_e32 v110, v127
	v_mov_b32_e32 v109, v127
	v_mov_b32_e32 v108, v127
	v_mov_b32_e32 v107, v127
	v_mov_b32_e32 v106, v127
	v_mov_b32_e32 v105, v127
	v_mov_b32_e32 v104, v127
	v_mov_b32_e32 v95, v127
	v_mov_b32_e32 v94, v127
	v_mov_b32_e32 v93, v127
	v_mov_b32_e32 v92, v127
	v_mov_b32_e32 v91, v127
	v_mov_b32_e32 v90, v127
	v_mov_b32_e32 v89, v127
	v_mov_b32_e32 v88, v127
	v_mov_b32_e32 v79, v127
	v_mov_b32_e32 v78, v127
	v_mov_b32_e32 v77, v127
	v_mov_b32_e32 v76, v127
	v_mov_b32_e32 v75, v127
	v_mov_b32_e32 v74, v127
	v_mov_b32_e32 v73, v127
	v_mov_b32_e32 v72, v127
	v_mov_b32_e32 v119, v127
	v_mov_b32_e32 v118, v127
	v_mov_b32_e32 v117, v127
	v_mov_b32_e32 v116, v127
	v_mov_b32_e32 v115, v127
	v_mov_b32_e32 v114, v127
	v_mov_b32_e32 v113, v127
	v_mov_b32_e32 v112, v127
	v_mov_b32_e32 v103, v127
	v_mov_b32_e32 v102, v127
	v_mov_b32_e32 v101, v127
	v_mov_b32_e32 v100, v127
	v_mov_b32_e32 v99, v127
	v_mov_b32_e32 v98, v127
	v_mov_b32_e32 v97, v127
	v_mov_b32_e32 v96, v127
	v_mov_b32_e32 v87, v127
	v_mov_b32_e32 v86, v127
	v_mov_b32_e32 v85, v127
	v_mov_b32_e32 v84, v127
	v_mov_b32_e32 v83, v127
	v_mov_b32_e32 v82, v127
	v_mov_b32_e32 v81, v127
	v_mov_b32_e32 v80, v127
	v_mov_b32_e32 v71, v127
	v_mov_b32_e32 v70, v127
	v_mov_b32_e32 v69, v127
	v_mov_b32_e32 v68, v127
	v_mov_b32_e32 v67, v127
	v_mov_b32_e32 v66, v127
	v_mov_b32_e32 v65, v127
	v_mov_b32_e32 v64, v127
	v_mov_b32_e32 v63, v127
	v_mov_b32_e32 v62, v127
	v_mov_b32_e32 v61, v127
	v_mov_b32_e32 v60, v127
	v_mov_b32_e32 v59, v127
	v_mov_b32_e32 v58, v127
	v_mov_b32_e32 v57, v127
	v_mov_b32_e32 v56, v127
	v_mov_b32_e32 v47, v127
	v_mov_b32_e32 v46, v127
	v_mov_b32_e32 v45, v127
	v_mov_b32_e32 v44, v127
	v_mov_b32_e32 v43, v127
	v_mov_b32_e32 v42, v127
	v_mov_b32_e32 v41, v127
	v_mov_b32_e32 v40, v127
	v_mov_b32_e32 v31, v127
	v_mov_b32_e32 v30, v127
	v_mov_b32_e32 v29, v127
	v_mov_b32_e32 v28, v127
	v_mov_b32_e32 v27, v127
	v_mov_b32_e32 v26, v127
	v_mov_b32_e32 v25, v127
	v_mov_b32_e32 v24, v127
	v_mov_b32_e32 v15, v127
	v_mov_b32_e32 v14, v127
	v_mov_b32_e32 v13, v127
	v_mov_b32_e32 v12, v127
	v_mov_b32_e32 v11, v127
	v_mov_b32_e32 v10, v127
	v_mov_b32_e32 v9, v127
	v_mov_b32_e32 v8, v127
	v_mov_b32_e32 v55, v127
	v_mov_b32_e32 v54, v127
	v_mov_b32_e32 v53, v127
	v_mov_b32_e32 v52, v127
	v_mov_b32_e32 v51, v127
	v_mov_b32_e32 v50, v127
	v_mov_b32_e32 v49, v127
	v_mov_b32_e32 v48, v127
	v_mov_b32_e32 v39, v127
	v_mov_b32_e32 v38, v127
	v_mov_b32_e32 v37, v127
	v_mov_b32_e32 v36, v127
	v_mov_b32_e32 v35, v127
	v_mov_b32_e32 v34, v127
	v_mov_b32_e32 v33, v127
	v_mov_b32_e32 v32, v127
	v_mov_b32_e32 v23, v127
	v_mov_b32_e32 v22, v127
	v_mov_b32_e32 v21, v127
	v_mov_b32_e32 v20, v127
	v_mov_b32_e32 v19, v127
	v_mov_b32_e32 v18, v127
	v_mov_b32_e32 v17, v127
	v_mov_b32_e32 v16, v127
	v_mov_b32_e32 v7, v127
	v_mov_b32_e32 v6, v127
	v_mov_b32_e32 v5, v127
	v_mov_b32_e32 v4, v127
	v_mov_b32_e32 v3, v127
	v_mov_b32_e32 v2, v127
	v_mov_b32_e32 v1, v127
	v_mov_b32_e32 v0, v127
	s_cbranch_vccnz .LBB0_166
	s_add_u32 s42, s18, 0x100
	s_addc_u32 s43, s19, 0
	s_add_u32 s16, s16, 0x80
	v_mov_b32_e32 v0, 0
	s_addc_u32 s17, s17, 0
	s_mov_b32 s18, 0
	v_mov_b32_e32 v1, v0
	v_mov_b32_e32 v2, v0
	v_mov_b32_e32 v3, v0
	v_mov_b32_e32 v4, v0
	v_mov_b32_e32 v5, v0
	v_mov_b32_e32 v6, v0
	v_mov_b32_e32 v7, v0
	v_mov_b32_e32 v16, v0
	v_mov_b32_e32 v17, v0
	v_mov_b32_e32 v18, v0
	v_mov_b32_e32 v19, v0
	v_mov_b32_e32 v20, v0
	v_mov_b32_e32 v21, v0
	v_mov_b32_e32 v22, v0
	v_mov_b32_e32 v23, v0
	v_mov_b32_e32 v32, v0
	v_mov_b32_e32 v33, v0
	v_mov_b32_e32 v34, v0
	v_mov_b32_e32 v35, v0
	v_mov_b32_e32 v36, v0
	v_mov_b32_e32 v37, v0
	v_mov_b32_e32 v38, v0
	v_mov_b32_e32 v39, v0
	v_mov_b32_e32 v48, v0
	v_mov_b32_e32 v49, v0
	v_mov_b32_e32 v50, v0
	v_mov_b32_e32 v51, v0
	v_mov_b32_e32 v52, v0
	v_mov_b32_e32 v53, v0
	v_mov_b32_e32 v54, v0
	v_mov_b32_e32 v55, v0
	v_mov_b32_e32 v8, v0
	v_mov_b32_e32 v9, v0
	v_mov_b32_e32 v10, v0
	v_mov_b32_e32 v11, v0
	v_mov_b32_e32 v12, v0
	v_mov_b32_e32 v13, v0
	v_mov_b32_e32 v14, v0
	v_mov_b32_e32 v15, v0
	v_mov_b32_e32 v24, v0
	v_mov_b32_e32 v25, v0
	v_mov_b32_e32 v26, v0
	v_mov_b32_e32 v27, v0
	v_mov_b32_e32 v28, v0
	v_mov_b32_e32 v29, v0
	v_mov_b32_e32 v30, v0
	v_mov_b32_e32 v31, v0
	v_mov_b32_e32 v40, v0
	v_mov_b32_e32 v41, v0
	v_mov_b32_e32 v42, v0
	v_mov_b32_e32 v43, v0
	v_mov_b32_e32 v44, v0
	v_mov_b32_e32 v45, v0
	v_mov_b32_e32 v46, v0
	v_mov_b32_e32 v47, v0
	v_mov_b32_e32 v56, v0
	v_mov_b32_e32 v57, v0
	v_mov_b32_e32 v58, v0
	v_mov_b32_e32 v59, v0
	v_mov_b32_e32 v60, v0
	v_mov_b32_e32 v61, v0
	v_mov_b32_e32 v62, v0
	v_mov_b32_e32 v63, v0
	v_mov_b32_e32 v64, v0
	v_mov_b32_e32 v65, v0
	v_mov_b32_e32 v66, v0
	v_mov_b32_e32 v67, v0
	v_mov_b32_e32 v68, v0
	v_mov_b32_e32 v69, v0
	v_mov_b32_e32 v70, v0
	v_mov_b32_e32 v71, v0
	v_mov_b32_e32 v80, v0
	v_mov_b32_e32 v81, v0
	v_mov_b32_e32 v82, v0
	v_mov_b32_e32 v83, v0
	v_mov_b32_e32 v84, v0
	v_mov_b32_e32 v85, v0
	v_mov_b32_e32 v86, v0
	v_mov_b32_e32 v87, v0
	v_mov_b32_e32 v96, v0
	v_mov_b32_e32 v97, v0
	v_mov_b32_e32 v98, v0
	v_mov_b32_e32 v99, v0
	v_mov_b32_e32 v100, v0
	v_mov_b32_e32 v101, v0
	v_mov_b32_e32 v102, v0
	v_mov_b32_e32 v103, v0
	v_mov_b32_e32 v112, v0
	v_mov_b32_e32 v113, v0
	v_mov_b32_e32 v114, v0
	v_mov_b32_e32 v115, v0
	v_mov_b32_e32 v116, v0
	v_mov_b32_e32 v117, v0
	v_mov_b32_e32 v118, v0
	v_mov_b32_e32 v119, v0
	v_mov_b32_e32 v72, v0
	v_mov_b32_e32 v73, v0
	v_mov_b32_e32 v74, v0
	v_mov_b32_e32 v75, v0
	v_mov_b32_e32 v76, v0
	v_mov_b32_e32 v77, v0
	v_mov_b32_e32 v78, v0
	v_mov_b32_e32 v79, v0
	v_mov_b32_e32 v88, v0
	v_mov_b32_e32 v89, v0
	v_mov_b32_e32 v90, v0
	v_mov_b32_e32 v91, v0
	v_mov_b32_e32 v92, v0
	v_mov_b32_e32 v93, v0
	v_mov_b32_e32 v94, v0
	v_mov_b32_e32 v95, v0
	v_mov_b32_e32 v104, v0
	v_mov_b32_e32 v105, v0
	v_mov_b32_e32 v106, v0
	v_mov_b32_e32 v107, v0
	v_mov_b32_e32 v108, v0
	v_mov_b32_e32 v109, v0
	v_mov_b32_e32 v110, v0
	v_mov_b32_e32 v111, v0
	v_mov_b32_e32 v120, v0
	v_mov_b32_e32 v121, v0
	v_mov_b32_e32 v122, v0
	v_mov_b32_e32 v123, v0
	v_mov_b32_e32 v124, v0
	v_mov_b32_e32 v125, v0
	v_mov_b32_e32 v126, v0
	v_mov_b32_e32 v127, v0
	s_mov_b64 s[48:49], 0x80
	v_add_u32_e32 v224, 0x10000, v146
	v_add_u32_e32 v225, 0x14000, v146
	v_add_u32_e32 v226, 0x18000, v146
	v_add_u32_e32 v227, 0x1c000, v146
; #define PG8_STAGE(bufoff, gbase, voff) do { _Pragma("unroll") for (int _i = 0; _i < 2; ++_i) \
;         __builtin_amdgcn_global_load_lds((const unsigned*)((const char*)(gbase) + (voff)[_i]), (LAS unsigned*)(lds + (bufoff) + ldsw + _i * 8192), 16, 0, 0); } while (0)
; #define PG8_LDA(dst, b, h) do { _Pragma("unroll") for (int m = 0; m < 4; ++m) _Pragma("unroll") for (int k = 0; k < 2; ++k) dst[m][k] = *(const LAS bf16x8*)(lds + PG8_SA(b, h) + aoff + m * 2048 + k * 1024); } while (0)
; #define PG8_LDB(dst, b, h) do { _Pragma("unroll") for (int n = 0; n < 2; ++n) _Pragma("unroll") for (int k = 0; k < 2; ++k) dst[n][k] = *(const LAS bf16x8*)(lds + PG8_SB(b, h) + boff + n * 2048 + k * 1024); } while (0)
; #define PG8_WAIT_V(n) asm volatile("s_waitcnt vmcnt(" #n ")" ::: "memory")
; #define PG8_WAIT_L(n) asm volatile("s_waitcnt lgkmcnt(" #n ")" ::: "memory")
; #define PG8_BAR __builtin_amdgcn_s_barrier()
; #define PG8_SCHED __builtin_amdgcn_sched_barrier(0)
; template <class Epi>
; __device__ __forceinline__ void gemm_phase(LAS unsigned char* lds, const Gemm g, const StaticOrder& S, const Epi& E) {
;     ...
;         const bool has_next = S.next(ui + 1, nxt);
;         const char* nA = has_next ? (const char*)g.A + (size_t)nxt.pm * tstep : cA; const char* nB = has_next ? (const char*)g.Bt + (size_t)nxt.pn * tstep : cB;
;         for (int t = 0; t < nt; t += 2) {
;             const bool last = (t == nt - 2);
;             const char* a1 = cA + (size_t)(t + 1) * kstep;
;             const char* a2 = last ? nA : cA + (size_t)(t + 2) * kstep; const char* b2 = last ? nB : cB + (size_t)(t + 2) * kstep;
;             const char* a3 = a2 + kstep; const char* b3 = b2 + kstep;
;             PG8_LDB(B0, 0, 0); PG8_SCHED; PG8_LDA(At, 0, 0); PG8_STAGE(PG8_SA(1, 1), a1 + hstep, voffA);
;             PG8_WAIT_L(8); PG8_BAR; PG8_WAIT_L(0); PG8_MMA(0, 0, At, B0); PG8_BAR; PG8_SCHED;
;             PG8_LDB(B1, 0, 1); PG8_STAGE(PG8_SB(0, 0), b2, voffB);
;             PG8_BAR; PG8_WAIT_L(0); PG8_MMA(0, 1, At, B1); PG8_BAR;
;             PG8_LDA(At, 0, 1); PG8_STAGE(PG8_SA(0, 0), a2, voffA);
;             PG8_BAR; PG8_WAIT_L(0); PG8_MMA(1, 0, At, B0); PG8_BAR; PG8_SCHED;
;             PG8_STAGE(PG8_SB(0, 1), b2 + hstep, voffB);
;             PG8_WAIT_V(6); PG8_BAR; PG8_MMA(1, 1, At, B1); PG8_BAR;
.LBB0_165:
	s_add_i32 s44, s18, 2
	s_add_u32 s20, s16, 0x80
	s_addc_u32 s19, s17, 0
	s_add_i32 s45, 0, 0x10000
	ds_read_b128 v[138:141], v224
	ds_read_b128 v[152:155], v224 offset:1024
	ds_read_b128 v[156:159], v224 offset:2048
	ds_read_b128 v[160:163], v224 offset:3072
	s_cmp_eq_u32 s35, s18
	s_cselect_b32 s18, s10, s20
	s_cselect_b32 s19, s11, s19
	s_cselect_b32 s21, s13, s43
	s_cselect_b32 s20, s12, s42
	s_add_i32 m0, s27, 0xc000
	ds_read_b128 v[164:167], v150
	ds_read_b128 v[168:171], v150 offset:1024
	ds_read_b128 v[172:175], v150 offset:2048
	ds_read_b128 v[176:179], v150 offset:3072
	ds_read_b128 v[180:183], v150 offset:4096
	ds_read_b128 v[184:187], v150 offset:5120
	ds_read_b128 v[188:191], v150 offset:6144
	global_load_lds_dwordx4 v136, s[16:17]
	s_add_i32 m0, s27, 0xe000
	ds_read_b128 v[202:205], v150 offset:7168
	global_load_lds_dwordx4 v134, s[16:17]
	s_waitcnt lgkmcnt(8)
	s_barrier
	s_waitcnt lgkmcnt(0)
	v_mfma_f32_16x16x32_bf16 v[124:127], v[138:141], v[164:167], v[124:127]
	v_mfma_f32_16x16x32_bf16 v[120:123], v[156:159], v[164:167], v[120:123]
	v_mfma_f32_16x16x32_bf16 v[108:111], v[138:141], v[172:175], v[108:111]
	v_mfma_f32_16x16x32_bf16 v[104:107], v[156:159], v[172:175], v[104:107]
	v_mfma_f32_16x16x32_bf16 v[92:95], v[138:141], v[180:183], v[92:95]
	v_mfma_f32_16x16x32_bf16 v[88:91], v[156:159], v[180:183], v[88:91]
	v_mfma_f32_16x16x32_bf16 v[76:79], v[138:141], v[188:191], v[76:79]
	v_mfma_f32_16x16x32_bf16 v[72:75], v[156:159], v[188:191], v[72:75]
	v_mfma_f32_16x16x32_bf16 v[124:127], v[152:155], v[168:171], v[124:127]
	v_mfma_f32_16x16x32_bf16 v[120:123], v[160:163], v[168:171], v[120:123]
	v_mfma_f32_16x16x32_bf16 v[108:111], v[152:155], v[176:179], v[108:111]
	v_mfma_f32_16x16x32_bf16 v[104:107], v[160:163], v[176:179], v[104:107]
	v_mfma_f32_16x16x32_bf16 v[92:95], v[152:155], v[184:187], v[92:95]
	v_mfma_f32_16x16x32_bf16 v[88:91], v[160:163], v[184:187], v[88:91]
	v_mfma_f32_16x16x32_bf16 v[76:79], v[152:155], v[202:205], v[76:79]
	v_mfma_f32_16x16x32_bf16 v[72:75], v[160:163], v[202:205], v[72:75]
	s_barrier
	s_add_i32 s46, 0, 0x14000
	s_add_i32 s45, s45, s26
	ds_read_b128 v[206:209], v225
	ds_read_b128 v[210:213], v225 offset:1024
	s_add_u32 s80, s20, 0x80
	s_addc_u32 s81, s21, 0
	s_mov_b32 m0, s45
	ds_read_b128 v[218:221], v225 offset:3072
	global_load_lds_dwordx4 v194, s[20:21]
	s_add_i32 m0, s45, 0x2000
	ds_read_b128 v[214:217], v225 offset:2048
	global_load_lds_dwordx4 v132, s[20:21]
	s_barrier
	s_waitcnt lgkmcnt(0)
	v_mfma_f32_16x16x32_bf16 v[116:119], v[206:209], v[164:167], v[116:119]
	v_mfma_f32_16x16x32_bf16 v[112:115], v[214:217], v[164:167], v[112:115]
	v_mfma_f32_16x16x32_bf16 v[100:103], v[206:209], v[172:175], v[100:103]
	v_mfma_f32_16x16x32_bf16 v[96:99], v[214:217], v[172:175], v[96:99]
	v_mfma_f32_16x16x32_bf16 v[84:87], v[206:209], v[180:183], v[84:87]
	v_mfma_f32_16x16x32_bf16 v[80:83], v[214:217], v[180:183], v[80:83]
	v_mfma_f32_16x16x32_bf16 v[68:71], v[206:209], v[188:191], v[68:71]
	v_mfma_f32_16x16x32_bf16 v[64:67], v[214:217], v[188:191], v[64:67]
	v_mfma_f32_16x16x32_bf16 v[116:119], v[210:213], v[168:171], v[116:119]
	v_mfma_f32_16x16x32_bf16 v[112:115], v[218:221], v[168:171], v[112:115]
	v_mfma_f32_16x16x32_bf16 v[100:103], v[210:213], v[176:179], v[100:103]
	v_mfma_f32_16x16x32_bf16 v[96:99], v[218:221], v[176:179], v[96:99]
	v_mfma_f32_16x16x32_bf16 v[84:87], v[210:213], v[184:187], v[84:87]
	v_mfma_f32_16x16x32_bf16 v[80:83], v[218:221], v[184:187], v[80:83]
	v_mfma_f32_16x16x32_bf16 v[68:71], v[210:213], v[202:205], v[68:71]
	v_mfma_f32_16x16x32_bf16 v[64:67], v[218:221], v[202:205], v[64:67]
	s_mov_b32 m0, s27
	s_add_u32 s82, s18, 0x80
	s_addc_u32 s83, s19, 0
	s_barrier
	ds_read_b128 v[164:167], v150 offset:16384
	ds_read_b128 v[168:171], v150 offset:17408
	ds_read_b128 v[172:175], v150 offset:18432
	ds_read_b128 v[176:179], v150 offset:19456
	ds_read_b128 v[180:183], v150 offset:20480
	ds_read_b128 v[184:187], v150 offset:21504
	ds_read_b128 v[188:191], v150 offset:22528
	global_load_lds_dwordx4 v128, s[18:19]
	s_mov_b32 m0, s28
	ds_read_b128 v[202:205], v150 offset:23552
	global_load_lds_dwordx4 v130, s[18:19]
	s_barrier
	s_waitcnt lgkmcnt(0)
	v_mfma_f32_16x16x32_bf16 v[60:63], v[138:141], v[164:167], v[60:63]
	v_mfma_f32_16x16x32_bf16 v[56:59], v[156:159], v[164:167], v[56:59]
	v_mfma_f32_16x16x32_bf16 v[44:47], v[138:141], v[172:175], v[44:47]
	v_mfma_f32_16x16x32_bf16 v[40:43], v[156:159], v[172:175], v[40:43]
	v_mfma_f32_16x16x32_bf16 v[28:31], v[138:141], v[180:183], v[28:31]
	v_mfma_f32_16x16x32_bf16 v[24:27], v[156:159], v[180:183], v[24:27]
	v_mfma_f32_16x16x32_bf16 v[12:15], v[138:141], v[188:191], v[12:15]
	v_mfma_f32_16x16x32_bf16 v[8:11], v[156:159], v[188:191], v[8:11]
	v_mfma_f32_16x16x32_bf16 v[60:63], v[152:155], v[168:171], v[60:63]
	v_mfma_f32_16x16x32_bf16 v[56:59], v[160:163], v[168:171], v[56:59]
	v_mfma_f32_16x16x32_bf16 v[44:47], v[152:155], v[176:179], v[44:47]
	v_mfma_f32_16x16x32_bf16 v[40:43], v[160:163], v[176:179], v[40:43]
	v_mfma_f32_16x16x32_bf16 v[28:31], v[152:155], v[184:187], v[28:31]
	v_mfma_f32_16x16x32_bf16 v[24:27], v[160:163], v[184:187], v[24:27]
	v_mfma_f32_16x16x32_bf16 v[12:15], v[152:155], v[202:205], v[12:15]
	v_mfma_f32_16x16x32_bf16 v[8:11], v[160:163], v[202:205], v[8:11]
	s_barrier
	s_add_u32 s20, s20, s2
	s_addc_u32 s21, s21, s3
	s_add_i32 s45, s46, s26
	s_add_u32 s84, s20, 0x80
	s_mov_b32 m0, s45
	s_addc_u32 s85, s21, 0
	global_load_lds_dwordx4 v194, s[20:21]
	s_add_i32 m0, s45, 0x2000
	s_nop 0
	global_load_lds_dwordx4 v132, s[20:21]
	s_waitcnt vmcnt(6)
	s_barrier
; #define PG8_STAGE(bufoff, gbase, voff) do { _Pragma("unroll") for (int _i = 0; _i < 2; ++_i) \
;         __builtin_amdgcn_global_load_lds((const unsigned*)((const char*)(gbase) + (voff)[_i]), (LAS unsigned*)(lds + (bufoff) + ldsw + _i * 8192), 16, 0, 0); } while (0)
; #define PG8_LDA(dst, b, h) do { _Pragma("unroll") for (int m = 0; m < 4; ++m) _Pragma("unroll") for (int k = 0; k < 2; ++k) dst[m][k] = *(const LAS bf16x8*)(lds + PG8_SA(b, h) + aoff + m * 2048 + k * 1024); } while (0)
; #define PG8_LDB(dst, b, h) do { _Pragma("unroll") for (int n = 0; n < 2; ++n) _Pragma("unroll") for (int k = 0; k < 2; ++k) dst[n][k] = *(const LAS bf16x8*)(lds + PG8_SB(b, h) + boff + n * 2048 + k * 1024); } while (0)
; #define PG8_MMA(ai, bj, At, Bt) do { __builtin_amdgcn_s_setprio(1); _Pragma("unroll") for (int m = 0; m < 4; ++m) _Pragma("unroll") for (int n = 0; n < 2; ++n) _Pragma("unroll") for (int k = 0; k < 2; ++k) \
;         acc[ai][bj][m][n] = __builtin_amdgcn_mfma_f32_16x16x32_bf16(Bt[n][k], At[m][k], acc[ai][bj][m][n], 0, 0, 0); __builtin_amdgcn_s_setprio(0); } while (0)
; #define PG8_WAIT_V(n) asm volatile("s_waitcnt vmcnt(" #n ")" ::: "memory")
; #define PG8_WAIT_L(n) asm volatile("s_waitcnt lgkmcnt(" #n ")" ::: "memory")
; #define PG8_BAR __builtin_amdgcn_s_barrier()
; #define PG8_SCHED __builtin_amdgcn_sched_barrier(0)
; template <class Epi>
; __device__ __forceinline__ void gemm_phase(LAS unsigned char* lds, const Gemm g, const StaticOrder& S, const Epi& E) {
;     ...
;             PG8_WAIT_V(6); PG8_BAR; PG8_MMA(1, 1, At, B1); PG8_BAR;
;             PG8_LDB(B0, 1, 0); PG8_SCHED; PG8_LDA(At, 1, 0); PG8_STAGE(PG8_SA(0, 1), a2 + hstep, voffA);
;             PG8_WAIT_L(8); PG8_BAR; PG8_WAIT_L(0); PG8_MMA(0, 0, At, B0); PG8_BAR; PG8_SCHED;
;             PG8_LDB(B1, 1, 1); PG8_STAGE(PG8_SB(1, 0), b3, voffB);
	v_mfma_f32_16x16x32_bf16 v[52:55], v[206:209], v[164:167], v[52:55]
	v_mfma_f32_16x16x32_bf16 v[48:51], v[214:217], v[164:167], v[48:51]
	v_mfma_f32_16x16x32_bf16 v[36:39], v[206:209], v[172:175], v[36:39]
	v_mfma_f32_16x16x32_bf16 v[32:35], v[214:217], v[172:175], v[32:35]
	v_mfma_f32_16x16x32_bf16 v[20:23], v[206:209], v[180:183], v[20:23]
	v_mfma_f32_16x16x32_bf16 v[16:19], v[214:217], v[180:183], v[16:19]
	v_mfma_f32_16x16x32_bf16 v[4:7], v[206:209], v[188:191], v[4:7]
	v_mfma_f32_16x16x32_bf16 v[0:3], v[214:217], v[188:191], v[0:3]
	v_mfma_f32_16x16x32_bf16 v[52:55], v[210:213], v[168:171], v[52:55]
	v_mfma_f32_16x16x32_bf16 v[48:51], v[218:221], v[168:171], v[48:51]
	v_mfma_f32_16x16x32_bf16 v[36:39], v[210:213], v[176:179], v[36:39]
	v_mfma_f32_16x16x32_bf16 v[32:35], v[218:221], v[176:179], v[32:35]
	v_mfma_f32_16x16x32_bf16 v[20:23], v[210:213], v[184:187], v[20:23]
	v_mfma_f32_16x16x32_bf16 v[16:19], v[218:221], v[184:187], v[16:19]
	v_mfma_f32_16x16x32_bf16 v[4:7], v[210:213], v[202:205], v[4:7]
	v_mfma_f32_16x16x32_bf16 v[0:3], v[218:221], v[202:205], v[0:3]
	s_add_i32 s20, 0, 0x18000
	s_barrier
	ds_read_b128 v[138:141], v226
	ds_read_b128 v[152:155], v226 offset:1024
	ds_read_b128 v[156:159], v226 offset:2048
	ds_read_b128 v[160:163], v226 offset:3072
	s_add_u32 s18, s18, s2
	s_addc_u32 s19, s19, s3
	s_mov_b32 m0, s29
	ds_read_b128 v[164:167], v150 offset:32768
	ds_read_b128 v[168:171], v150 offset:33792
	ds_read_b128 v[172:175], v150 offset:34816
	ds_read_b128 v[176:179], v150 offset:35840
	ds_read_b128 v[180:183], v150 offset:36864
	ds_read_b128 v[184:187], v150 offset:37888
	ds_read_b128 v[188:191], v150 offset:38912
	global_load_lds_dwordx4 v128, s[18:19]
	s_mov_b32 m0, s30
	ds_read_b128 v[202:205], v150 offset:39936
	global_load_lds_dwordx4 v130, s[18:19]
	s_waitcnt lgkmcnt(8)
	s_barrier
	s_waitcnt lgkmcnt(0)
	v_mfma_f32_16x16x32_bf16 v[124:127], v[138:141], v[164:167], v[124:127]
	v_mfma_f32_16x16x32_bf16 v[120:123], v[156:159], v[164:167], v[120:123]
	v_mfma_f32_16x16x32_bf16 v[108:111], v[138:141], v[172:175], v[108:111]
	v_mfma_f32_16x16x32_bf16 v[104:107], v[156:159], v[172:175], v[104:107]
	v_mfma_f32_16x16x32_bf16 v[92:95], v[138:141], v[180:183], v[92:95]
	v_mfma_f32_16x16x32_bf16 v[88:91], v[156:159], v[180:183], v[88:91]
	v_mfma_f32_16x16x32_bf16 v[76:79], v[138:141], v[188:191], v[76:79]
	v_mfma_f32_16x16x32_bf16 v[72:75], v[156:159], v[188:191], v[72:75]
	v_mfma_f32_16x16x32_bf16 v[124:127], v[152:155], v[168:171], v[124:127]
	v_mfma_f32_16x16x32_bf16 v[120:123], v[160:163], v[168:171], v[120:123]
	v_mfma_f32_16x16x32_bf16 v[108:111], v[152:155], v[176:179], v[108:111]
	v_mfma_f32_16x16x32_bf16 v[104:107], v[160:163], v[176:179], v[104:107]
	v_mfma_f32_16x16x32_bf16 v[92:95], v[152:155], v[184:187], v[92:95]
	v_mfma_f32_16x16x32_bf16 v[88:91], v[160:163], v[184:187], v[88:91]
	v_mfma_f32_16x16x32_bf16 v[76:79], v[152:155], v[202:205], v[76:79]
	v_mfma_f32_16x16x32_bf16 v[72:75], v[160:163], v[202:205], v[72:75]
	s_barrier
	s_add_i32 s18, 0, 0x1c000
	s_add_i32 s19, s20, s26
	s_mov_b32 m0, s19
	ds_read_b128 v[206:209], v227
	ds_read_b128 v[210:213], v227 offset:1024
	ds_read_b128 v[214:217], v227 offset:2048
	global_load_lds_dwordx4 v194, s[80:81]
	s_add_i32 m0, s19, 0x2000
	ds_read_b128 v[218:221], v227 offset:3072
	global_load_lds_dwordx4 v132, s[80:81]
	s_barrier
; #define PG8_STAGE(bufoff, gbase, voff) do { _Pragma("unroll") for (int _i = 0; _i < 2; ++_i) \
;         __builtin_amdgcn_global_load_lds((const unsigned*)((const char*)(gbase) + (voff)[_i]), (LAS unsigned*)(lds + (bufoff) + ldsw + _i * 8192), 16, 0, 0); } while (0)
; #define PG8_LDA(dst, b, h) do { _Pragma("unroll") for (int m = 0; m < 4; ++m) _Pragma("unroll") for (int k = 0; k < 2; ++k) dst[m][k] = *(const LAS bf16x8*)(lds + PG8_SA(b, h) + aoff + m * 2048 + k * 1024); } while (0)
; #define PG8_MMA(ai, bj, At, Bt) do { __builtin_amdgcn_s_setprio(1); _Pragma("unroll") for (int m = 0; m < 4; ++m) _Pragma("unroll") for (int n = 0; n < 2; ++n) _Pragma("unroll") for (int k = 0; k < 2; ++k) \
;         acc[ai][bj][m][n] = __builtin_amdgcn_mfma_f32_16x16x32_bf16(Bt[n][k], At[m][k], acc[ai][bj][m][n], 0, 0, 0); __builtin_amdgcn_s_setprio(0); } while (0)
; #define PG8_WAIT_V(n) asm volatile("s_waitcnt vmcnt(" #n ")" ::: "memory")
; #define PG8_WAIT_L(n) asm volatile("s_waitcnt lgkmcnt(" #n ")" ::: "memory")
; #define PG8_BAR __builtin_amdgcn_s_barrier()
; #define PG8_SCHED __builtin_amdgcn_sched_barrier(0)
; template <class Epi>
; __device__ __forceinline__ void gemm_phase(LAS unsigned char* lds, const Gemm g, const StaticOrder& S, const Epi& E) {
;     ...
;             PG8_BAR; PG8_WAIT_L(0); PG8_MMA(0, 1, At, B1); PG8_BAR;
;             PG8_LDA(At, 1, 1); PG8_STAGE(PG8_SA(1, 0), a3, voffA);
;             PG8_BAR; PG8_WAIT_L(0); PG8_MMA(1, 0, At, B0); PG8_BAR; PG8_SCHED;
;             PG8_STAGE(PG8_SB(1, 1), b3 + hstep, voffB);
;             PG8_WAIT_V(6); PG8_BAR; PG8_MMA(1, 1, At, B1); PG8_BAR;
;         }
	s_waitcnt lgkmcnt(0)
	v_mfma_f32_16x16x32_bf16 v[116:119], v[206:209], v[164:167], v[116:119]
	v_mfma_f32_16x16x32_bf16 v[112:115], v[214:217], v[164:167], v[112:115]
	v_mfma_f32_16x16x32_bf16 v[100:103], v[206:209], v[172:175], v[100:103]
	v_mfma_f32_16x16x32_bf16 v[96:99], v[214:217], v[172:175], v[96:99]
	v_mfma_f32_16x16x32_bf16 v[84:87], v[206:209], v[180:183], v[84:87]
	v_mfma_f32_16x16x32_bf16 v[80:83], v[214:217], v[180:183], v[80:83]
	v_mfma_f32_16x16x32_bf16 v[68:71], v[206:209], v[188:191], v[68:71]
	v_mfma_f32_16x16x32_bf16 v[64:67], v[214:217], v[188:191], v[64:67]
	v_mfma_f32_16x16x32_bf16 v[116:119], v[210:213], v[168:171], v[116:119]
	v_mfma_f32_16x16x32_bf16 v[112:115], v[218:221], v[168:171], v[112:115]
	v_mfma_f32_16x16x32_bf16 v[100:103], v[210:213], v[176:179], v[100:103]
	v_mfma_f32_16x16x32_bf16 v[96:99], v[218:221], v[176:179], v[96:99]
	v_mfma_f32_16x16x32_bf16 v[84:87], v[210:213], v[184:187], v[84:87]
	v_mfma_f32_16x16x32_bf16 v[80:83], v[218:221], v[184:187], v[80:83]
	v_mfma_f32_16x16x32_bf16 v[68:71], v[210:213], v[202:205], v[68:71]
	v_mfma_f32_16x16x32_bf16 v[64:67], v[218:221], v[202:205], v[64:67]
	s_mov_b32 m0, s31
	s_barrier
	ds_read_b128 v[164:167], v150 offset:49152
	ds_read_b128 v[168:171], v150 offset:50176
	ds_read_b128 v[172:175], v150 offset:51200
	ds_read_b128 v[176:179], v150 offset:52224
	ds_read_b128 v[180:183], v150 offset:53248
	ds_read_b128 v[184:187], v150 offset:54272
	ds_read_b128 v[188:191], v150 offset:55296
	global_load_lds_dwordx4 v128, s[82:83]
	s_mov_b32 m0, s33
	ds_read_b128 v[202:205], v150 offset:56320
	global_load_lds_dwordx4 v130, s[82:83]
	s_barrier
	s_waitcnt lgkmcnt(0)
	v_mfma_f32_16x16x32_bf16 v[60:63], v[138:141], v[164:167], v[60:63]
	v_mfma_f32_16x16x32_bf16 v[56:59], v[156:159], v[164:167], v[56:59]
	v_mfma_f32_16x16x32_bf16 v[44:47], v[138:141], v[172:175], v[44:47]
	v_mfma_f32_16x16x32_bf16 v[40:43], v[156:159], v[172:175], v[40:43]
	v_mfma_f32_16x16x32_bf16 v[28:31], v[138:141], v[180:183], v[28:31]
	v_mfma_f32_16x16x32_bf16 v[24:27], v[156:159], v[180:183], v[24:27]
	v_mfma_f32_16x16x32_bf16 v[12:15], v[138:141], v[188:191], v[12:15]
	v_mfma_f32_16x16x32_bf16 v[8:11], v[156:159], v[188:191], v[8:11]
	v_mfma_f32_16x16x32_bf16 v[60:63], v[152:155], v[168:171], v[60:63]
	v_mfma_f32_16x16x32_bf16 v[56:59], v[160:163], v[168:171], v[56:59]
	v_mfma_f32_16x16x32_bf16 v[44:47], v[152:155], v[176:179], v[44:47]
	v_mfma_f32_16x16x32_bf16 v[40:43], v[160:163], v[176:179], v[40:43]
	v_mfma_f32_16x16x32_bf16 v[28:31], v[152:155], v[184:187], v[28:31]
	v_mfma_f32_16x16x32_bf16 v[24:27], v[160:163], v[184:187], v[24:27]
	v_mfma_f32_16x16x32_bf16 v[12:15], v[152:155], v[202:205], v[12:15]
	v_mfma_f32_16x16x32_bf16 v[8:11], v[160:163], v[202:205], v[8:11]
	s_barrier
	s_add_i32 s18, s18, s26
	s_mov_b32 m0, s18
	s_nop 0
	global_load_lds_dwordx4 v194, s[84:85]
	s_add_i32 m0, s18, 0x2000
	s_nop 0
	global_load_lds_dwordx4 v132, s[84:85]
	s_waitcnt vmcnt(6)
	s_barrier
	v_mfma_f32_16x16x32_bf16 v[52:55], v[206:209], v[164:167], v[52:55]
	v_mfma_f32_16x16x32_bf16 v[48:51], v[214:217], v[164:167], v[48:51]
	v_mfma_f32_16x16x32_bf16 v[36:39], v[206:209], v[172:175], v[36:39]
	v_mfma_f32_16x16x32_bf16 v[32:35], v[214:217], v[172:175], v[32:35]
	v_mfma_f32_16x16x32_bf16 v[20:23], v[206:209], v[180:183], v[20:23]
	v_mfma_f32_16x16x32_bf16 v[16:19], v[214:217], v[180:183], v[16:19]
	v_mfma_f32_16x16x32_bf16 v[4:7], v[206:209], v[188:191], v[4:7]
	v_mfma_f32_16x16x32_bf16 v[0:3], v[214:217], v[188:191], v[0:3]
	v_mfma_f32_16x16x32_bf16 v[52:55], v[210:213], v[168:171], v[52:55]
	v_mfma_f32_16x16x32_bf16 v[48:51], v[218:221], v[168:171], v[48:51]
	v_mfma_f32_16x16x32_bf16 v[36:39], v[210:213], v[176:179], v[36:39]
	v_mfma_f32_16x16x32_bf16 v[32:35], v[218:221], v[176:179], v[32:35]
	v_mfma_f32_16x16x32_bf16 v[20:23], v[210:213], v[184:187], v[20:23]
	v_mfma_f32_16x16x32_bf16 v[16:19], v[218:221], v[184:187], v[16:19]
	v_mfma_f32_16x16x32_bf16 v[4:7], v[210:213], v[202:205], v[4:7]
	v_mfma_f32_16x16x32_bf16 v[0:3], v[218:221], v[202:205], v[0:3]
	s_add_u32 s42, s42, 0x100
	s_addc_u32 s43, s43, 0
	s_add_u32 s16, s16, 0x100
	s_addc_u32 s17, s17, 0
	s_cmp_ge_i32 s44, s34
	s_mov_b32 s18, s44
	s_barrier
	s_cbranch_scc0 .LBB0_165

; template <class Epi>
; __device__ __forceinline__ void gemm_phase(LAS unsigned char* lds, const Gemm g, const StaticOrder& S, const Epi& E) {
;     ...
;     f32x4 acc[2][2][4][2];
; #pragma unroll
;     for (int a = 0; a < 2; ++a)
; #pragma unroll
;         for (int b = 0; b < 2; ++b)
; #pragma unroll
;             for (int m = 0; m < 4; ++m)
; #pragma unroll
;                 for (int n = 0; n < 2; ++n) acc[a][b][m][n] = (f32x4){0.f, 0.f, 0.f, 0.f};
;     ...
; #pragma unroll
;         for (int a = 0; a < 2; ++a)
; #pragma unroll
;             for (int b = 0; b < 2; ++b)
; #pragma unroll
;                 for (int m = 0; m < 4; ++m)
; #pragma unroll
;                     for (int n = 0; n < 2; ++n) acc[a][b][m][n] = (f32x4){0.f, 0.f, 0.f, 0.f};
;         cur = nxt; cA = nA; cB = nB; ++ui;
.LBB0_526:
	v_mov_b32_e32 v127, 0
	s_andn2_b64 vcc, exec, s[6:7]
	v_mov_b32_e32 v126, v127
	v_mov_b32_e32 v125, v127
	v_mov_b32_e32 v124, v127
	v_mov_b32_e32 v123, v127
	v_mov_b32_e32 v122, v127
	v_mov_b32_e32 v121, v127
	v_mov_b32_e32 v120, v127
	v_mov_b32_e32 v111, v127
	v_mov_b32_e32 v110, v127
	v_mov_b32_e32 v109, v127
	v_mov_b32_e32 v108, v127
	v_mov_b32_e32 v107, v127
	v_mov_b32_e32 v106, v127
	v_mov_b32_e32 v105, v127
	v_mov_b32_e32 v104, v127
	v_mov_b32_e32 v95, v127
	v_mov_b32_e32 v94, v127
	v_mov_b32_e32 v93, v127
	v_mov_b32_e32 v92, v127
	v_mov_b32_e32 v91, v127
	v_mov_b32_e32 v90, v127
	v_mov_b32_e32 v89, v127
	v_mov_b32_e32 v88, v127
	v_mov_b32_e32 v79, v127
	v_mov_b32_e32 v78, v127
	v_mov_b32_e32 v77, v127
	v_mov_b32_e32 v76, v127
	v_mov_b32_e32 v75, v127
	v_mov_b32_e32 v74, v127
	v_mov_b32_e32 v73, v127
	v_mov_b32_e32 v72, v127
	v_mov_b32_e32 v119, v127
	v_mov_b32_e32 v118, v127
	v_mov_b32_e32 v117, v127
	v_mov_b32_e32 v116, v127
	v_mov_b32_e32 v115, v127
	v_mov_b32_e32 v114, v127
	v_mov_b32_e32 v113, v127
	v_mov_b32_e32 v112, v127
	v_mov_b32_e32 v103, v127
	v_mov_b32_e32 v102, v127
	v_mov_b32_e32 v101, v127
	v_mov_b32_e32 v100, v127
	v_mov_b32_e32 v99, v127
	v_mov_b32_e32 v98, v127
	v_mov_b32_e32 v97, v127
	v_mov_b32_e32 v96, v127
	v_mov_b32_e32 v87, v127
	v_mov_b32_e32 v86, v127
	v_mov_b32_e32 v85, v127
	v_mov_b32_e32 v84, v127
	v_mov_b32_e32 v83, v127
	v_mov_b32_e32 v82, v127
	v_mov_b32_e32 v81, v127
	v_mov_b32_e32 v80, v127
	v_mov_b32_e32 v71, v127
	v_mov_b32_e32 v70, v127
	v_mov_b32_e32 v69, v127
	v_mov_b32_e32 v68, v127
	v_mov_b32_e32 v67, v127
	v_mov_b32_e32 v66, v127
	v_mov_b32_e32 v65, v127
	v_mov_b32_e32 v64, v127
	v_mov_b32_e32 v63, v127
	v_mov_b32_e32 v62, v127
	v_mov_b32_e32 v61, v127
	v_mov_b32_e32 v60, v127
	v_mov_b32_e32 v59, v127
	v_mov_b32_e32 v58, v127
	v_mov_b32_e32 v57, v127
	v_mov_b32_e32 v56, v127
	v_mov_b32_e32 v47, v127
	v_mov_b32_e32 v46, v127
	v_mov_b32_e32 v45, v127
	v_mov_b32_e32 v44, v127
	v_mov_b32_e32 v43, v127
	v_mov_b32_e32 v42, v127
	v_mov_b32_e32 v41, v127
	v_mov_b32_e32 v40, v127
	v_mov_b32_e32 v31, v127
	v_mov_b32_e32 v30, v127
	v_mov_b32_e32 v29, v127
	v_mov_b32_e32 v28, v127
	v_mov_b32_e32 v27, v127
	v_mov_b32_e32 v26, v127
	v_mov_b32_e32 v25, v127
	v_mov_b32_e32 v24, v127
	v_mov_b32_e32 v15, v127
	v_mov_b32_e32 v14, v127
	v_mov_b32_e32 v13, v127
	v_mov_b32_e32 v12, v127
	v_mov_b32_e32 v11, v127
	v_mov_b32_e32 v10, v127
	v_mov_b32_e32 v9, v127
	v_mov_b32_e32 v8, v127
	v_mov_b32_e32 v55, v127
	v_mov_b32_e32 v54, v127
	v_mov_b32_e32 v53, v127
	v_mov_b32_e32 v52, v127
	v_mov_b32_e32 v51, v127
	v_mov_b32_e32 v50, v127
	v_mov_b32_e32 v49, v127
	v_mov_b32_e32 v48, v127
	v_mov_b32_e32 v39, v127
	v_mov_b32_e32 v38, v127
	v_mov_b32_e32 v37, v127
	v_mov_b32_e32 v36, v127
	v_mov_b32_e32 v35, v127
	v_mov_b32_e32 v34, v127
	v_mov_b32_e32 v33, v127
	v_mov_b32_e32 v32, v127
	v_mov_b32_e32 v23, v127
	v_mov_b32_e32 v22, v127
	v_mov_b32_e32 v21, v127
	v_mov_b32_e32 v20, v127
	v_mov_b32_e32 v19, v127
	v_mov_b32_e32 v18, v127
	v_mov_b32_e32 v17, v127
	v_mov_b32_e32 v16, v127
	v_mov_b32_e32 v7, v127
	v_mov_b32_e32 v6, v127
	v_mov_b32_e32 v5, v127
	v_mov_b32_e32 v4, v127
	v_mov_b32_e32 v3, v127
	v_mov_b32_e32 v2, v127
	v_mov_b32_e32 v1, v127
	v_mov_b32_e32 v0, v127
	s_cbranch_vccnz .LBB0_529
	s_add_u32 s40, s18, 0x100
	s_addc_u32 s41, s19, 0
	s_add_u32 s16, s16, 0x80
	v_mov_b32_e32 v0, 0
	s_addc_u32 s17, s17, 0
	s_mov_b32 s18, 0
	v_mov_b32_e32 v1, v0
	v_mov_b32_e32 v2, v0
	v_mov_b32_e32 v3, v0
	v_mov_b32_e32 v4, v0
	v_mov_b32_e32 v5, v0
	v_mov_b32_e32 v6, v0
	v_mov_b32_e32 v7, v0
	v_mov_b32_e32 v16, v0
	v_mov_b32_e32 v17, v0
	v_mov_b32_e32 v18, v0
	v_mov_b32_e32 v19, v0
	v_mov_b32_e32 v20, v0
	v_mov_b32_e32 v21, v0
	v_mov_b32_e32 v22, v0
	v_mov_b32_e32 v23, v0
	v_mov_b32_e32 v32, v0
	v_mov_b32_e32 v33, v0
	v_mov_b32_e32 v34, v0
	v_mov_b32_e32 v35, v0
	v_mov_b32_e32 v36, v0
	v_mov_b32_e32 v37, v0
	v_mov_b32_e32 v38, v0
	v_mov_b32_e32 v39, v0
	v_mov_b32_e32 v48, v0
	v_mov_b32_e32 v49, v0
	v_mov_b32_e32 v50, v0
	v_mov_b32_e32 v51, v0
	v_mov_b32_e32 v52, v0
	v_mov_b32_e32 v53, v0
	v_mov_b32_e32 v54, v0
	v_mov_b32_e32 v55, v0
	v_mov_b32_e32 v8, v0
	v_mov_b32_e32 v9, v0
	v_mov_b32_e32 v10, v0
	v_mov_b32_e32 v11, v0
	v_mov_b32_e32 v12, v0
	v_mov_b32_e32 v13, v0
	v_mov_b32_e32 v14, v0
	v_mov_b32_e32 v15, v0
	v_mov_b32_e32 v24, v0
	v_mov_b32_e32 v25, v0
	v_mov_b32_e32 v26, v0
	v_mov_b32_e32 v27, v0
	v_mov_b32_e32 v28, v0
	v_mov_b32_e32 v29, v0
	v_mov_b32_e32 v30, v0
	v_mov_b32_e32 v31, v0
	v_mov_b32_e32 v40, v0
	v_mov_b32_e32 v41, v0
	v_mov_b32_e32 v42, v0
	v_mov_b32_e32 v43, v0
	v_mov_b32_e32 v44, v0
	v_mov_b32_e32 v45, v0
	v_mov_b32_e32 v46, v0
	v_mov_b32_e32 v47, v0
	v_mov_b32_e32 v56, v0
	v_mov_b32_e32 v57, v0
	v_mov_b32_e32 v58, v0
	v_mov_b32_e32 v59, v0
	v_mov_b32_e32 v60, v0
	v_mov_b32_e32 v61, v0
	v_mov_b32_e32 v62, v0
	v_mov_b32_e32 v63, v0
	v_mov_b32_e32 v64, v0
	v_mov_b32_e32 v65, v0
	v_mov_b32_e32 v66, v0
	v_mov_b32_e32 v67, v0
	v_mov_b32_e32 v68, v0
	v_mov_b32_e32 v69, v0
	v_mov_b32_e32 v70, v0
	v_mov_b32_e32 v71, v0
	v_mov_b32_e32 v80, v0
	v_mov_b32_e32 v81, v0
	v_mov_b32_e32 v82, v0
	v_mov_b32_e32 v83, v0
	v_mov_b32_e32 v84, v0
	v_mov_b32_e32 v85, v0
	v_mov_b32_e32 v86, v0
	v_mov_b32_e32 v87, v0
	v_mov_b32_e32 v96, v0
	v_mov_b32_e32 v97, v0
	v_mov_b32_e32 v98, v0
	v_mov_b32_e32 v99, v0
	v_mov_b32_e32 v100, v0
	v_mov_b32_e32 v101, v0
	v_mov_b32_e32 v102, v0
	v_mov_b32_e32 v103, v0
	v_mov_b32_e32 v112, v0
	v_mov_b32_e32 v113, v0
	v_mov_b32_e32 v114, v0
	v_mov_b32_e32 v115, v0
	v_mov_b32_e32 v116, v0
	v_mov_b32_e32 v117, v0
	v_mov_b32_e32 v118, v0
	v_mov_b32_e32 v119, v0
	v_mov_b32_e32 v72, v0
	v_mov_b32_e32 v73, v0
	v_mov_b32_e32 v74, v0
	v_mov_b32_e32 v75, v0
	v_mov_b32_e32 v76, v0
	v_mov_b32_e32 v77, v0
	v_mov_b32_e32 v78, v0
	v_mov_b32_e32 v79, v0
	v_mov_b32_e32 v88, v0
	v_mov_b32_e32 v89, v0
	v_mov_b32_e32 v90, v0
	v_mov_b32_e32 v91, v0
	v_mov_b32_e32 v92, v0
	v_mov_b32_e32 v93, v0
	v_mov_b32_e32 v94, v0
	v_mov_b32_e32 v95, v0
	v_mov_b32_e32 v104, v0
	v_mov_b32_e32 v105, v0
	v_mov_b32_e32 v106, v0
	v_mov_b32_e32 v107, v0
	v_mov_b32_e32 v108, v0
	v_mov_b32_e32 v109, v0
	v_mov_b32_e32 v110, v0
	v_mov_b32_e32 v111, v0
	v_mov_b32_e32 v120, v0
	v_mov_b32_e32 v121, v0
	v_mov_b32_e32 v122, v0
	v_mov_b32_e32 v123, v0
	v_mov_b32_e32 v124, v0
	v_mov_b32_e32 v125, v0
	v_mov_b32_e32 v126, v0
	v_mov_b32_e32 v127, v0
	s_mov_b64 s[46:47], 0x80
	v_add_u32_e32 v224, 0x10000, v144
	v_add_u32_e32 v225, 0x14000, v144
	v_add_u32_e32 v226, 0x18000, v144
	v_add_u32_e32 v227, 0x1c000, v144
; #define PG8_STAGE(bufoff, gbase, voff) do { _Pragma("unroll") for (int _i = 0; _i < 2; ++_i) \
;         __builtin_amdgcn_global_load_lds((const unsigned*)((const char*)(gbase) + (voff)[_i]), (LAS unsigned*)(lds + (bufoff) + ldsw + _i * 8192), 16, 0, 0); } while (0)
; #define PG8_LDA(dst, b, h) do { _Pragma("unroll") for (int m = 0; m < 4; ++m) _Pragma("unroll") for (int k = 0; k < 2; ++k) dst[m][k] = *(const LAS bf16x8*)(lds + PG8_SA(b, h) + aoff + m * 2048 + k * 1024); } while (0)
; #define PG8_LDB(dst, b, h) do { _Pragma("unroll") for (int n = 0; n < 2; ++n) _Pragma("unroll") for (int k = 0; k < 2; ++k) dst[n][k] = *(const LAS bf16x8*)(lds + PG8_SB(b, h) + boff + n * 2048 + k * 1024); } while (0)
; #define PG8_WAIT_V(n) asm volatile("s_waitcnt vmcnt(" #n ")" ::: "memory")
; #define PG8_WAIT_L(n) asm volatile("s_waitcnt lgkmcnt(" #n ")" ::: "memory")
; #define PG8_BAR __builtin_amdgcn_s_barrier()
; #define PG8_SCHED __builtin_amdgcn_sched_barrier(0)
; template <class Epi>
; __device__ __forceinline__ void gemm_phase(LAS unsigned char* lds, const Gemm g, const StaticOrder& S, const Epi& E) {
;     ...
;         const bool has_next = S.next(ui + 1, nxt);
;         const char* nA = has_next ? (const char*)g.A + (size_t)nxt.pm * tstep : cA; const char* nB = has_next ? (const char*)g.Bt + (size_t)nxt.pn * tstep : cB;
;         for (int t = 0; t < nt; t += 2) {
;             const bool last = (t == nt - 2);
;             const char* a1 = cA + (size_t)(t + 1) * kstep;
;             const char* a2 = last ? nA : cA + (size_t)(t + 2) * kstep; const char* b2 = last ? nB : cB + (size_t)(t + 2) * kstep;
;             const char* a3 = a2 + kstep; const char* b3 = b2 + kstep;
;             PG8_LDB(B0, 0, 0); PG8_SCHED; PG8_LDA(At, 0, 0); PG8_STAGE(PG8_SA(1, 1), a1 + hstep, voffA);
;             PG8_WAIT_L(8); PG8_BAR; PG8_WAIT_L(0); PG8_MMA(0, 0, At, B0); PG8_BAR; PG8_SCHED;
;             PG8_LDB(B1, 0, 1); PG8_STAGE(PG8_SB(0, 0), b2, voffB);
;             PG8_BAR; PG8_WAIT_L(0); PG8_MMA(0, 1, At, B1); PG8_BAR;
;             PG8_LDA(At, 0, 1); PG8_STAGE(PG8_SA(0, 0), a2, voffA);
;             PG8_BAR; PG8_WAIT_L(0); PG8_MMA(1, 0, At, B0); PG8_BAR; PG8_SCHED;
;             PG8_STAGE(PG8_SB(0, 1), b2 + hstep, voffB);
;             PG8_WAIT_V(6); PG8_BAR; PG8_MMA(1, 1, At, B1); PG8_BAR;
.LBB0_528:
	s_add_i32 s42, s18, 2
	s_add_u32 s20, s16, 0x80
	s_addc_u32 s19, s17, 0
	s_add_i32 s43, 0, 0x10000
	ds_read_b128 v[138:141], v224
	ds_read_b128 v[150:153], v224 offset:1024
	ds_read_b128 v[154:157], v224 offset:2048
	ds_read_b128 v[158:161], v224 offset:3072
	s_cmp_eq_u32 s33, s18
	s_cselect_b32 s18, s10, s20
	s_cselect_b32 s19, s11, s19
	s_cselect_b32 s21, s13, s41
	s_cselect_b32 s20, s12, s40
	s_add_i32 m0, s25, 0xc000
	ds_read_b128 v[162:165], v148
	ds_read_b128 v[166:169], v148 offset:1024
	ds_read_b128 v[170:173], v148 offset:2048
	ds_read_b128 v[174:177], v148 offset:3072
	ds_read_b128 v[178:181], v148 offset:4096
	ds_read_b128 v[182:185], v148 offset:5120
	ds_read_b128 v[186:189], v148 offset:6144
	global_load_lds_dwordx4 v136, s[16:17]
	s_add_i32 m0, s25, 0xe000
	ds_read_b128 v[202:205], v148 offset:7168
	global_load_lds_dwordx4 v134, s[16:17]
	s_waitcnt lgkmcnt(8)
	s_barrier
	s_waitcnt lgkmcnt(0)
	v_mfma_f32_16x16x32_bf16 v[124:127], v[138:141], v[162:165], v[124:127]
	v_mfma_f32_16x16x32_bf16 v[120:123], v[154:157], v[162:165], v[120:123]
	v_mfma_f32_16x16x32_bf16 v[108:111], v[138:141], v[170:173], v[108:111]
	v_mfma_f32_16x16x32_bf16 v[104:107], v[154:157], v[170:173], v[104:107]
	v_mfma_f32_16x16x32_bf16 v[92:95], v[138:141], v[178:181], v[92:95]
	v_mfma_f32_16x16x32_bf16 v[88:91], v[154:157], v[178:181], v[88:91]
	v_mfma_f32_16x16x32_bf16 v[76:79], v[138:141], v[186:189], v[76:79]
	v_mfma_f32_16x16x32_bf16 v[72:75], v[154:157], v[186:189], v[72:75]
	v_mfma_f32_16x16x32_bf16 v[124:127], v[150:153], v[166:169], v[124:127]
	v_mfma_f32_16x16x32_bf16 v[120:123], v[158:161], v[166:169], v[120:123]
	v_mfma_f32_16x16x32_bf16 v[108:111], v[150:153], v[174:177], v[108:111]
	v_mfma_f32_16x16x32_bf16 v[104:107], v[158:161], v[174:177], v[104:107]
	v_mfma_f32_16x16x32_bf16 v[92:95], v[150:153], v[182:185], v[92:95]
	v_mfma_f32_16x16x32_bf16 v[88:91], v[158:161], v[182:185], v[88:91]
	v_mfma_f32_16x16x32_bf16 v[76:79], v[150:153], v[202:205], v[76:79]
	v_mfma_f32_16x16x32_bf16 v[72:75], v[158:161], v[202:205], v[72:75]
	s_barrier
	s_add_i32 s44, 0, 0x14000
	s_add_i32 s43, s43, s24
	s_add_u32 s80, s20, 0x80
	s_addc_u32 s81, s21, 0
	s_mov_b32 m0, s43
	ds_read_b128 v[206:209], v225
	ds_read_b128 v[210:213], v225 offset:1024
	ds_read_b128 v[214:217], v225 offset:2048
	global_load_lds_dwordx4 v194, s[20:21]
	s_add_i32 m0, s43, 0x2000
	ds_read_b128 v[218:221], v225 offset:3072
	global_load_lds_dwordx4 v132, s[20:21]
	s_barrier
	s_waitcnt lgkmcnt(0)
	v_mfma_f32_16x16x32_bf16 v[116:119], v[206:209], v[162:165], v[116:119]
	v_mfma_f32_16x16x32_bf16 v[112:115], v[214:217], v[162:165], v[112:115]
	v_mfma_f32_16x16x32_bf16 v[100:103], v[206:209], v[170:173], v[100:103]
	v_mfma_f32_16x16x32_bf16 v[96:99], v[214:217], v[170:173], v[96:99]
	v_mfma_f32_16x16x32_bf16 v[84:87], v[206:209], v[178:181], v[84:87]
	v_mfma_f32_16x16x32_bf16 v[80:83], v[214:217], v[178:181], v[80:83]
	v_mfma_f32_16x16x32_bf16 v[68:71], v[206:209], v[186:189], v[68:71]
	v_mfma_f32_16x16x32_bf16 v[64:67], v[214:217], v[186:189], v[64:67]
	v_mfma_f32_16x16x32_bf16 v[116:119], v[210:213], v[166:169], v[116:119]
	v_mfma_f32_16x16x32_bf16 v[112:115], v[218:221], v[166:169], v[112:115]
	v_mfma_f32_16x16x32_bf16 v[100:103], v[210:213], v[174:177], v[100:103]
	v_mfma_f32_16x16x32_bf16 v[96:99], v[218:221], v[174:177], v[96:99]
	v_mfma_f32_16x16x32_bf16 v[84:87], v[210:213], v[182:185], v[84:87]
	v_mfma_f32_16x16x32_bf16 v[80:83], v[218:221], v[182:185], v[80:83]
	v_mfma_f32_16x16x32_bf16 v[68:71], v[210:213], v[202:205], v[68:71]
	v_mfma_f32_16x16x32_bf16 v[64:67], v[218:221], v[202:205], v[64:67]
	s_mov_b32 m0, s25
	s_add_u32 s82, s18, 0x80
	s_addc_u32 s83, s19, 0
	s_barrier
	ds_read_b128 v[162:165], v148 offset:16384
	ds_read_b128 v[166:169], v148 offset:17408
	ds_read_b128 v[170:173], v148 offset:18432
	ds_read_b128 v[174:177], v148 offset:19456
	ds_read_b128 v[178:181], v148 offset:20480
	ds_read_b128 v[182:185], v148 offset:21504
	ds_read_b128 v[186:189], v148 offset:22528
	global_load_lds_dwordx4 v128, s[18:19]
	s_mov_b32 m0, s26
	ds_read_b128 v[202:205], v148 offset:23552
	global_load_lds_dwordx4 v130, s[18:19]
	s_barrier
	s_waitcnt lgkmcnt(0)
	v_mfma_f32_16x16x32_bf16 v[60:63], v[138:141], v[162:165], v[60:63]
	v_mfma_f32_16x16x32_bf16 v[56:59], v[154:157], v[162:165], v[56:59]
	v_mfma_f32_16x16x32_bf16 v[44:47], v[138:141], v[170:173], v[44:47]
	v_mfma_f32_16x16x32_bf16 v[40:43], v[154:157], v[170:173], v[40:43]
	v_mfma_f32_16x16x32_bf16 v[28:31], v[138:141], v[178:181], v[28:31]
	v_mfma_f32_16x16x32_bf16 v[24:27], v[154:157], v[178:181], v[24:27]
	v_mfma_f32_16x16x32_bf16 v[12:15], v[138:141], v[186:189], v[12:15]
	v_mfma_f32_16x16x32_bf16 v[8:11], v[154:157], v[186:189], v[8:11]
	v_mfma_f32_16x16x32_bf16 v[60:63], v[150:153], v[166:169], v[60:63]
	v_mfma_f32_16x16x32_bf16 v[56:59], v[158:161], v[166:169], v[56:59]
	v_mfma_f32_16x16x32_bf16 v[44:47], v[150:153], v[174:177], v[44:47]
	v_mfma_f32_16x16x32_bf16 v[40:43], v[158:161], v[174:177], v[40:43]
	v_mfma_f32_16x16x32_bf16 v[28:31], v[150:153], v[182:185], v[28:31]
	v_mfma_f32_16x16x32_bf16 v[24:27], v[158:161], v[182:185], v[24:27]
	v_mfma_f32_16x16x32_bf16 v[12:15], v[150:153], v[202:205], v[12:15]
	v_mfma_f32_16x16x32_bf16 v[8:11], v[158:161], v[202:205], v[8:11]
	s_barrier
	s_add_u32 s20, s20, s2
	s_addc_u32 s21, s21, s3
	s_add_i32 s43, s44, s24
	s_add_u32 s84, s20, 0x80
	s_mov_b32 m0, s43
	s_addc_u32 s85, s21, 0
	global_load_lds_dwordx4 v194, s[20:21]
	s_add_i32 m0, s43, 0x2000
	s_nop 0
	global_load_lds_dwordx4 v132, s[20:21]
	s_waitcnt vmcnt(6)
	s_barrier
; #define PG8_STAGE(bufoff, gbase, voff) do { _Pragma("unroll") for (int _i = 0; _i < 2; ++_i) \
;         __builtin_amdgcn_global_load_lds((const unsigned*)((const char*)(gbase) + (voff)[_i]), (LAS unsigned*)(lds + (bufoff) + ldsw + _i * 8192), 16, 0, 0); } while (0)
; #define PG8_LDA(dst, b, h) do { _Pragma("unroll") for (int m = 0; m < 4; ++m) _Pragma("unroll") for (int k = 0; k < 2; ++k) dst[m][k] = *(const LAS bf16x8*)(lds + PG8_SA(b, h) + aoff + m * 2048 + k * 1024); } while (0)
; #define PG8_LDB(dst, b, h) do { _Pragma("unroll") for (int n = 0; n < 2; ++n) _Pragma("unroll") for (int k = 0; k < 2; ++k) dst[n][k] = *(const LAS bf16x8*)(lds + PG8_SB(b, h) + boff + n * 2048 + k * 1024); } while (0)
; #define PG8_MMA(ai, bj, At, Bt) do { __builtin_amdgcn_s_setprio(1); _Pragma("unroll") for (int m = 0; m < 4; ++m) _Pragma("unroll") for (int n = 0; n < 2; ++n) _Pragma("unroll") for (int k = 0; k < 2; ++k) \
;         acc[ai][bj][m][n] = __builtin_amdgcn_mfma_f32_16x16x32_bf16(Bt[n][k], At[m][k], acc[ai][bj][m][n], 0, 0, 0); __builtin_amdgcn_s_setprio(0); } while (0)
; #define PG8_WAIT_V(n) asm volatile("s_waitcnt vmcnt(" #n ")" ::: "memory")
; #define PG8_WAIT_L(n) asm volatile("s_waitcnt lgkmcnt(" #n ")" ::: "memory")
; #define PG8_BAR __builtin_amdgcn_s_barrier()
; #define PG8_SCHED __builtin_amdgcn_sched_barrier(0)
; template <class Epi>
; __device__ __forceinline__ void gemm_phase(LAS unsigned char* lds, const Gemm g, const StaticOrder& S, const Epi& E) {
;     ...
;             PG8_WAIT_V(6); PG8_BAR; PG8_MMA(1, 1, At, B1); PG8_BAR;
;             PG8_LDB(B0, 1, 0); PG8_SCHED; PG8_LDA(At, 1, 0); PG8_STAGE(PG8_SA(0, 1), a2 + hstep, voffA);
;             PG8_WAIT_L(8); PG8_BAR; PG8_WAIT_L(0); PG8_MMA(0, 0, At, B0); PG8_BAR; PG8_SCHED;
;             PG8_LDB(B1, 1, 1); PG8_STAGE(PG8_SB(1, 0), b3, voffB);
	v_mfma_f32_16x16x32_bf16 v[52:55], v[206:209], v[162:165], v[52:55]
	v_mfma_f32_16x16x32_bf16 v[48:51], v[214:217], v[162:165], v[48:51]
	v_mfma_f32_16x16x32_bf16 v[36:39], v[206:209], v[170:173], v[36:39]
	v_mfma_f32_16x16x32_bf16 v[32:35], v[214:217], v[170:173], v[32:35]
	v_mfma_f32_16x16x32_bf16 v[20:23], v[206:209], v[178:181], v[20:23]
	v_mfma_f32_16x16x32_bf16 v[16:19], v[214:217], v[178:181], v[16:19]
	v_mfma_f32_16x16x32_bf16 v[4:7], v[206:209], v[186:189], v[4:7]
	v_mfma_f32_16x16x32_bf16 v[0:3], v[214:217], v[186:189], v[0:3]
	v_mfma_f32_16x16x32_bf16 v[52:55], v[210:213], v[166:169], v[52:55]
	v_mfma_f32_16x16x32_bf16 v[48:51], v[218:221], v[166:169], v[48:51]
	v_mfma_f32_16x16x32_bf16 v[36:39], v[210:213], v[174:177], v[36:39]
	v_mfma_f32_16x16x32_bf16 v[32:35], v[218:221], v[174:177], v[32:35]
	v_mfma_f32_16x16x32_bf16 v[20:23], v[210:213], v[182:185], v[20:23]
	v_mfma_f32_16x16x32_bf16 v[16:19], v[218:221], v[182:185], v[16:19]
	v_mfma_f32_16x16x32_bf16 v[4:7], v[210:213], v[202:205], v[4:7]
	v_mfma_f32_16x16x32_bf16 v[0:3], v[218:221], v[202:205], v[0:3]
	s_add_i32 s20, 0, 0x18000
	s_barrier
	ds_read_b128 v[138:141], v226
	ds_read_b128 v[150:153], v226 offset:1024
	ds_read_b128 v[154:157], v226 offset:2048
	ds_read_b128 v[158:161], v226 offset:3072
	s_add_u32 s18, s18, s2
	s_addc_u32 s19, s19, s3
	s_mov_b32 m0, s27
	ds_read_b128 v[162:165], v148 offset:32768
	ds_read_b128 v[166:169], v148 offset:33792
	ds_read_b128 v[170:173], v148 offset:34816
	ds_read_b128 v[174:177], v148 offset:35840
	ds_read_b128 v[178:181], v148 offset:36864
	ds_read_b128 v[182:185], v148 offset:37888
	ds_read_b128 v[186:189], v148 offset:38912
	global_load_lds_dwordx4 v128, s[18:19]
	s_mov_b32 m0, s28
	ds_read_b128 v[202:205], v148 offset:39936
	global_load_lds_dwordx4 v130, s[18:19]
	s_waitcnt lgkmcnt(8)
	s_barrier
	s_waitcnt lgkmcnt(0)
	v_mfma_f32_16x16x32_bf16 v[124:127], v[138:141], v[162:165], v[124:127]
	v_mfma_f32_16x16x32_bf16 v[120:123], v[154:157], v[162:165], v[120:123]
	v_mfma_f32_16x16x32_bf16 v[108:111], v[138:141], v[170:173], v[108:111]
	v_mfma_f32_16x16x32_bf16 v[104:107], v[154:157], v[170:173], v[104:107]
	v_mfma_f32_16x16x32_bf16 v[92:95], v[138:141], v[178:181], v[92:95]
	v_mfma_f32_16x16x32_bf16 v[88:91], v[154:157], v[178:181], v[88:91]
	v_mfma_f32_16x16x32_bf16 v[76:79], v[138:141], v[186:189], v[76:79]
	v_mfma_f32_16x16x32_bf16 v[72:75], v[154:157], v[186:189], v[72:75]
	v_mfma_f32_16x16x32_bf16 v[124:127], v[150:153], v[166:169], v[124:127]
	v_mfma_f32_16x16x32_bf16 v[120:123], v[158:161], v[166:169], v[120:123]
	v_mfma_f32_16x16x32_bf16 v[108:111], v[150:153], v[174:177], v[108:111]
	v_mfma_f32_16x16x32_bf16 v[104:107], v[158:161], v[174:177], v[104:107]
	v_mfma_f32_16x16x32_bf16 v[92:95], v[150:153], v[182:185], v[92:95]
	v_mfma_f32_16x16x32_bf16 v[88:91], v[158:161], v[182:185], v[88:91]
	v_mfma_f32_16x16x32_bf16 v[76:79], v[150:153], v[202:205], v[76:79]
	v_mfma_f32_16x16x32_bf16 v[72:75], v[158:161], v[202:205], v[72:75]
	s_barrier
	s_add_i32 s18, 0, 0x1c000
	s_add_i32 s19, s20, s24
	s_mov_b32 m0, s19
	ds_read_b128 v[206:209], v227
	ds_read_b128 v[210:213], v227 offset:1024
	ds_read_b128 v[214:217], v227 offset:2048
	global_load_lds_dwordx4 v194, s[80:81]
	s_add_i32 m0, s19, 0x2000
	ds_read_b128 v[218:221], v227 offset:3072
	global_load_lds_dwordx4 v132, s[80:81]
	s_barrier
; #define PG8_STAGE(bufoff, gbase, voff) do { _Pragma("unroll") for (int _i = 0; _i < 2; ++_i) \
;         __builtin_amdgcn_global_load_lds((const unsigned*)((const char*)(gbase) + (voff)[_i]), (LAS unsigned*)(lds + (bufoff) + ldsw + _i * 8192), 16, 0, 0); } while (0)
; #define PG8_LDA(dst, b, h) do { _Pragma("unroll") for (int m = 0; m < 4; ++m) _Pragma("unroll") for (int k = 0; k < 2; ++k) dst[m][k] = *(const LAS bf16x8*)(lds + PG8_SA(b, h) + aoff + m * 2048 + k * 1024); } while (0)
; #define PG8_MMA(ai, bj, At, Bt) do { __builtin_amdgcn_s_setprio(1); _Pragma("unroll") for (int m = 0; m < 4; ++m) _Pragma("unroll") for (int n = 0; n < 2; ++n) _Pragma("unroll") for (int k = 0; k < 2; ++k) \
;         acc[ai][bj][m][n] = __builtin_amdgcn_mfma_f32_16x16x32_bf16(Bt[n][k], At[m][k], acc[ai][bj][m][n], 0, 0, 0); __builtin_amdgcn_s_setprio(0); } while (0)
; #define PG8_WAIT_V(n) asm volatile("s_waitcnt vmcnt(" #n ")" ::: "memory")
; #define PG8_WAIT_L(n) asm volatile("s_waitcnt lgkmcnt(" #n ")" ::: "memory")
; #define PG8_BAR __builtin_amdgcn_s_barrier()
; #define PG8_SCHED __builtin_amdgcn_sched_barrier(0)
; template <class Epi>
; __device__ __forceinline__ void gemm_phase(LAS unsigned char* lds, const Gemm g, const StaticOrder& S, const Epi& E) {
;     ...
;             PG8_BAR; PG8_WAIT_L(0); PG8_MMA(0, 1, At, B1); PG8_BAR;
;             PG8_LDA(At, 1, 1); PG8_STAGE(PG8_SA(1, 0), a3, voffA);
;             PG8_BAR; PG8_WAIT_L(0); PG8_MMA(1, 0, At, B0); PG8_BAR; PG8_SCHED;
;             PG8_STAGE(PG8_SB(1, 1), b3 + hstep, voffB);
;             PG8_WAIT_V(6); PG8_BAR; PG8_MMA(1, 1, At, B1); PG8_BAR;
;         }
	s_waitcnt lgkmcnt(0)
	v_mfma_f32_16x16x32_bf16 v[116:119], v[206:209], v[162:165], v[116:119]
	v_mfma_f32_16x16x32_bf16 v[112:115], v[214:217], v[162:165], v[112:115]
	v_mfma_f32_16x16x32_bf16 v[100:103], v[206:209], v[170:173], v[100:103]
	v_mfma_f32_16x16x32_bf16 v[96:99], v[214:217], v[170:173], v[96:99]
	v_mfma_f32_16x16x32_bf16 v[84:87], v[206:209], v[178:181], v[84:87]
	v_mfma_f32_16x16x32_bf16 v[80:83], v[214:217], v[178:181], v[80:83]
	v_mfma_f32_16x16x32_bf16 v[68:71], v[206:209], v[186:189], v[68:71]
	v_mfma_f32_16x16x32_bf16 v[64:67], v[214:217], v[186:189], v[64:67]
	v_mfma_f32_16x16x32_bf16 v[116:119], v[210:213], v[166:169], v[116:119]
	v_mfma_f32_16x16x32_bf16 v[112:115], v[218:221], v[166:169], v[112:115]
	v_mfma_f32_16x16x32_bf16 v[100:103], v[210:213], v[174:177], v[100:103]
	v_mfma_f32_16x16x32_bf16 v[96:99], v[218:221], v[174:177], v[96:99]
	v_mfma_f32_16x16x32_bf16 v[84:87], v[210:213], v[182:185], v[84:87]
	v_mfma_f32_16x16x32_bf16 v[80:83], v[218:221], v[182:185], v[80:83]
	v_mfma_f32_16x16x32_bf16 v[68:71], v[210:213], v[202:205], v[68:71]
	v_mfma_f32_16x16x32_bf16 v[64:67], v[218:221], v[202:205], v[64:67]
	s_mov_b32 m0, s29
	s_barrier
	ds_read_b128 v[162:165], v148 offset:49152
	ds_read_b128 v[166:169], v148 offset:50176
	ds_read_b128 v[170:173], v148 offset:51200
	ds_read_b128 v[174:177], v148 offset:52224
	ds_read_b128 v[178:181], v148 offset:53248
	ds_read_b128 v[182:185], v148 offset:54272
	ds_read_b128 v[186:189], v148 offset:55296
	global_load_lds_dwordx4 v128, s[82:83]
	s_mov_b32 m0, s30
	ds_read_b128 v[202:205], v148 offset:56320
	global_load_lds_dwordx4 v130, s[82:83]
	s_barrier
	s_waitcnt lgkmcnt(0)
	v_mfma_f32_16x16x32_bf16 v[60:63], v[138:141], v[162:165], v[60:63]
	v_mfma_f32_16x16x32_bf16 v[56:59], v[154:157], v[162:165], v[56:59]
	v_mfma_f32_16x16x32_bf16 v[44:47], v[138:141], v[170:173], v[44:47]
	v_mfma_f32_16x16x32_bf16 v[40:43], v[154:157], v[170:173], v[40:43]
	v_mfma_f32_16x16x32_bf16 v[28:31], v[138:141], v[178:181], v[28:31]
	v_mfma_f32_16x16x32_bf16 v[24:27], v[154:157], v[178:181], v[24:27]
	v_mfma_f32_16x16x32_bf16 v[12:15], v[138:141], v[186:189], v[12:15]
	v_mfma_f32_16x16x32_bf16 v[8:11], v[154:157], v[186:189], v[8:11]
	v_mfma_f32_16x16x32_bf16 v[60:63], v[150:153], v[166:169], v[60:63]
	v_mfma_f32_16x16x32_bf16 v[56:59], v[158:161], v[166:169], v[56:59]
	v_mfma_f32_16x16x32_bf16 v[44:47], v[150:153], v[174:177], v[44:47]
	v_mfma_f32_16x16x32_bf16 v[40:43], v[158:161], v[174:177], v[40:43]
	v_mfma_f32_16x16x32_bf16 v[28:31], v[150:153], v[182:185], v[28:31]
	v_mfma_f32_16x16x32_bf16 v[24:27], v[158:161], v[182:185], v[24:27]
	v_mfma_f32_16x16x32_bf16 v[12:15], v[150:153], v[202:205], v[12:15]
	v_mfma_f32_16x16x32_bf16 v[8:11], v[158:161], v[202:205], v[8:11]
	s_barrier
	s_add_i32 s18, s18, s24
	s_mov_b32 m0, s18
	s_nop 0
	global_load_lds_dwordx4 v194, s[84:85]
	s_add_i32 m0, s18, 0x2000
	s_nop 0
	global_load_lds_dwordx4 v132, s[84:85]
	s_waitcnt vmcnt(6)
	s_barrier
	v_mfma_f32_16x16x32_bf16 v[52:55], v[206:209], v[162:165], v[52:55]
	v_mfma_f32_16x16x32_bf16 v[48:51], v[214:217], v[162:165], v[48:51]
	v_mfma_f32_16x16x32_bf16 v[36:39], v[206:209], v[170:173], v[36:39]
	v_mfma_f32_16x16x32_bf16 v[32:35], v[214:217], v[170:173], v[32:35]
	v_mfma_f32_16x16x32_bf16 v[20:23], v[206:209], v[178:181], v[20:23]
	v_mfma_f32_16x16x32_bf16 v[16:19], v[214:217], v[178:181], v[16:19]
	v_mfma_f32_16x16x32_bf16 v[4:7], v[206:209], v[186:189], v[4:7]
	v_mfma_f32_16x16x32_bf16 v[0:3], v[214:217], v[186:189], v[0:3]
	v_mfma_f32_16x16x32_bf16 v[52:55], v[210:213], v[166:169], v[52:55]
	v_mfma_f32_16x16x32_bf16 v[48:51], v[218:221], v[166:169], v[48:51]
	v_mfma_f32_16x16x32_bf16 v[36:39], v[210:213], v[174:177], v[36:39]
	v_mfma_f32_16x16x32_bf16 v[32:35], v[218:221], v[174:177], v[32:35]
	v_mfma_f32_16x16x32_bf16 v[20:23], v[210:213], v[182:185], v[20:23]
	v_mfma_f32_16x16x32_bf16 v[16:19], v[218:221], v[182:185], v[16:19]
	v_mfma_f32_16x16x32_bf16 v[4:7], v[210:213], v[202:205], v[4:7]
	v_mfma_f32_16x16x32_bf16 v[0:3], v[218:221], v[202:205], v[0:3]
	s_add_u32 s40, s40, 0x100
	s_addc_u32 s41, s41, 0
	s_add_u32 s16, s16, 0x100
	s_addc_u32 s17, s17, 0
	s_cmp_ge_i32 s42, s31
	s_mov_b32 s18, s42
	s_barrier
	s_cbranch_scc0 .LBB0_528
